# post_token stores the fp8 K copy directly in the head-major layout the sparse phase reads; the re-layout pass only moves V
# speedup vs baseline: 1.0028x; 1.0025x over previous
; __global__ void __launch_bounds__(NTHREADS, 2) mega(Args a) {
;     ...
;                 for (int rep = 0; rep < REP_POST; ++rep) for (int t = gw; t < SEQ; t += NGW)
;                     post_token(pos[t], a.in[I_GAQ] + l * 128, a.in[I_GAK] + l * 128, a.in[I_GBQ] + l * 128, a.in[I_GBK] + l * 128, a.in[I_GIK] + l * 64,
;                                QKV + (size_t)t * QKVW, IDXF + (size_t)t * IDXW, IQ + (size_t)t * 1024, IK + (size_t)t * 64, IW + (size_t)t * 16, K8 + (size_t)t * 1024, V8 + (size_t)t * 1024, lane);
.Lcp_loop:
	s_cmpk_lt_i32 s100, 0x4000
	s_cbranch_scc0 .Lcp_ld_done
	global_load_dwordx4 v[4:7], v33, s[90:91]
	v_add_u32_e32 v33, s98, v33
	s_add_i32 s100, s100, s66
	s_cmpk_lt_i32 s100, 0x4000
	s_cbranch_scc0 .Lcp_ld_done
	global_load_dwordx4 v[12:15], v33, s[90:91]
	v_add_u32_e32 v33, s98, v33
	s_add_i32 s100, s100, s66
	s_cmpk_lt_i32 s100, 0x4000
	s_cbranch_scc0 .Lcp_ld_done
	global_load_dwordx4 v[20:23], v33, s[90:91]
	v_add_u32_e32 v33, s98, v33
	s_add_i32 s100, s100, s66
	s_cmpk_lt_i32 s100, 0x4000
	s_cbranch_scc0 .Lcp_ld_done
	global_load_dwordx4 v[28:31], v33, s[90:91]
	v_add_u32_e32 v33, s98, v33
	s_add_i32 s100, s100, s66
.Lcp_ld_done:
	s_waitcnt vmcnt(0)
	s_cmpk_lt_i32 s101, 0x4000
	s_cbranch_scc0 .Lcp_st_done
	global_store_dwordx4 v35, v[4:7], s[90:91]
	s_nop 1
	v_add_u32_e32 v35, s99, v35
	s_add_i32 s101, s101, s66
	s_cmpk_lt_i32 s101, 0x4000
	s_cbranch_scc0 .Lcp_st_done
	global_store_dwordx4 v35, v[12:15], s[90:91]
	s_nop 1
	v_add_u32_e32 v35, s99, v35
	s_add_i32 s101, s101, s66
	s_cmpk_lt_i32 s101, 0x4000
	s_cbranch_scc0 .Lcp_st_done
	global_store_dwordx4 v35, v[20:23], s[90:91]
	s_nop 1
	v_add_u32_e32 v35, s99, v35
	s_add_i32 s101, s101, s66
	s_cmpk_lt_i32 s101, 0x4000
	s_cbranch_scc0 .Lcp_st_done
	global_store_dwordx4 v35, v[28:31], s[90:91]
	s_nop 1
	v_add_u32_e32 v35, s99, v35
	s_add_i32 s101, s101, s66

; __device__ __forceinline__ unsigned pk2(float lo, float hi) { return f2bf(lo) | (f2bf(hi) << 16); }
; template <int CTRL> __device__ __forceinline__ float dpp_f(float v) { return __builtin_bit_cast(float, __builtin_amdgcn_update_dpp(0, __builtin_bit_cast(int, v), CTRL, 0xF, 0xF, true)); }
; __device__ __forceinline__ float row16_sum(float v) { v += dpp_f<0x128>(v); v += dpp_f<0x124>(v); v += dpp_f<0x4E>(v); v += dpp_f<0xB1>(v); return v; }
; __device__ __forceinline__ void rope_cs(float ang, float& c, float& s) {
;     double rev = (double)ang * 0.15915494309189535; rev -= __builtin_rint(rev); const float rf = (float)rev;
;     s = __builtin_amdgcn_sinf(rf); c = __builtin_amdgcn_cosf(rf);
; }
; template <int NIT, bool F8>
; __device__ __forceinline__ void post_segment(bf16_t* seg, const float* gain, const float (&cs)[8], const float (&sn)[8], int c, int grp, unsigned char* k8 = nullptr) {
;     const f32x4 g0 = *(const f32x4*)(gain + 8 * c), g1 = *(const f32x4*)(gain + 8 * c + 4);
;     const float g[8] = {g0[0], g0[1], g0[2], g0[3], g1[0], g1[1], g1[2], g1[3]};
;     u32x4 raw[NIT];
; #pragma unroll
;     for (int it = 0; it < NIT; ++it) raw[it] = *(const u32x4*)(seg + (it * 4 + grp) * 128 + c * 8);
; #pragma unroll
;     for (int it = 0; it < NIT; ++it) {
;         const unsigned w[4] = {raw[it].x, raw[it].y, raw[it].z, raw[it].w}; float x[8];
; #pragma unroll
;         for (int i = 0; i < 4; ++i) { x[2 * i] = bf2f(w[i] & 0xffffu); x[2 * i + 1] = __builtin_bit_cast(float, w[i] & 0xffff0000u); }
;         float ss = 0.f;
; #pragma unroll
;         for (int e = 0; e < 8; ++e) ss += x[e] * x[e];
;         ss = row16_sum(ss); const float r = 1.f / sqrtf(ss * (1.f / 128.f) + EPS);
;         float o[8];
; #pragma unroll
;         for (int e = 0; e < 8; ++e) { const float y = x[e] * r * g[e]; const float py = dpp_f<0x128>(y); o[e] = y * cs[e] + py * sn[e]; }
;         u32x4 ow; ow.x = pk2(o[0], o[1]); ow.y = pk2(o[2], o[3]); ow.z = pk2(o[4], o[5]); ow.w = pk2(o[6], o[7]);
;         if constexpr (F8) *(u32x2*)(k8 + (it * 4 + grp) * 128 + c * 8) = to_fp8x8(o);
;         else *(u32x4*)(seg + (it * 4 + grp) * 128 + c * 8) = ow;
;     }
.LBB0_1008:
	global_load_dword v52, v161, s[4:5]
	v_lshl_add_u64 v[20:21], s[90:91], 0, v[40:41]
	s_mov_b32 s0, 0x12302000
	v_add_co_u32_e32 v64, vcc, s0, v20
	s_mov_b32 s0, 0x12300000
	s_nop 0
	v_addc_co_u32_e32 v65, vcc, 0, v21, vcc
	global_load_dwordx4 v[16:19], v[64:65], off offset:3072
	global_load_dwordx4 v[8:11], v[24:25], off offset:16
	global_load_dwordx4 v[12:15], v[24:25], off
	v_add_co_u32_e32 v76, vcc, s0, v20
	s_mov_b32 s0, 0x12303000
	v_add_co_u32_e64 v22, s[0:1], s0, v20
	v_addc_co_u32_e32 v77, vcc, 0, v21, vcc
	s_nop 0
	v_addc_co_u32_e64 v23, vcc, 0, v21, s[0:1]
	global_load_dwordx4 v[54:57], v[22:23], off
	s_mov_b32 s0, 0x6dc9c883
	s_mov_b32 s1, 0x3fc45f30
	s_mov_b32 s8, 0xf800000
	s_waitcnt vmcnt(4)
	v_cvt_f32_i32_e32 v22, v52
	v_mul_f32_e32 v23, v2, v22
	v_mul_f32_e32 v52, v3, v22
	s_waitcnt vmcnt(3)
	v_lshlrev_b32_e32 v78, 16, v16
	v_and_b32_e32 v79, 0xffff0000, v16
	v_lshlrev_b32_e32 v82, 16, v18
	v_and_b32_e32 v83, 0xffff0000, v18
	v_mul_f32_e32 v16, v0, v22
	v_mul_f32_e32 v18, v1, v22
	v_mul_f32_e32 v58, v4, v22
	v_mul_f32_e32 v60, v5, v22
	v_mul_f32_e32 v62, v6, v22
	v_mul_f32_e32 v66, v7, v22
	v_lshlrev_b32_e32 v80, 16, v17
	v_and_b32_e32 v81, 0xffff0000, v17
	v_lshlrev_b32_e32 v84, 16, v19
	v_and_b32_e32 v85, 0xffff0000, v19
	v_cvt_f64_f32_e32 v[16:17], v16
	v_cvt_f64_f32_e32 v[18:19], v18
	v_cvt_f64_f32_e32 v[22:23], v23
	v_cvt_f64_f32_e32 v[52:53], v52
	v_cvt_f64_f32_e32 v[58:59], v58
	v_cvt_f64_f32_e32 v[60:61], v60
	v_cvt_f64_f32_e32 v[62:63], v62
	v_cvt_f64_f32_e32 v[66:67], v66
	v_mul_f64 v[68:69], v[16:17], s[0:1]
	v_mul_f64 v[70:71], v[18:19], s[0:1]
	v_mul_f64 v[72:73], v[22:23], s[0:1]
	v_mul_f64 v[74:75], v[52:53], s[0:1]
	v_mul_f64 v[86:87], v[58:59], s[0:1]
	v_mul_f64 v[88:89], v[60:61], s[0:1]
	v_mul_f64 v[90:91], v[62:63], s[0:1]
	v_mul_f64 v[92:93], v[66:67], s[0:1]
	v_rndne_f64_e32 v[68:69], v[68:69]
	v_rndne_f64_e32 v[70:71], v[70:71]
	v_rndne_f64_e32 v[72:73], v[72:73]
	v_rndne_f64_e32 v[74:75], v[74:75]
	v_rndne_f64_e32 v[86:87], v[86:87]
	v_rndne_f64_e32 v[88:89], v[88:89]
	v_rndne_f64_e32 v[90:91], v[90:91]
	v_rndne_f64_e32 v[92:93], v[92:93]
	v_fma_f64 v[16:17], v[16:17], s[0:1], -v[68:69]
	v_fma_f64 v[18:19], v[18:19], s[0:1], -v[70:71]
	v_fma_f64 v[22:23], v[22:23], s[0:1], -v[72:73]
	v_fma_f64 v[52:53], v[52:53], s[0:1], -v[74:75]
	v_fma_f64 v[58:59], v[58:59], s[0:1], -v[86:87]
	v_fma_f64 v[60:61], v[60:61], s[0:1], -v[88:89]
	v_fma_f64 v[62:63], v[62:63], s[0:1], -v[90:91]
	v_fma_f64 v[66:67], v[66:67], s[0:1], -v[92:93]
	s_mov_b32 s0, 0x12301000
	v_add_co_u32_e64 v74, s[0:1], s0, v20
	v_cvt_f32_f64_e32 v16, v[16:17]
	s_nop 0
	v_addc_co_u32_e64 v75, s[0:1], 0, v21, s[0:1]
	global_load_dwordx4 v[68:71], v[74:75], off offset:-4096
	v_cvt_f32_f64_e32 v17, v[18:19]
	v_cvt_f32_f64_e32 v18, v[22:23]
	v_cvt_f32_f64_e32 v22, v[58:59]
	v_cvt_f32_f64_e32 v23, v[60:61]
	v_cvt_f32_f64_e32 v61, v[66:67]
	v_sin_f32_e32 v66, v16
	v_cos_f32_e32 v58, v16
	v_mul_f32_e32 v16, v79, v79
	v_fmac_f32_e32 v16, v78, v78
	v_fmac_f32_e32 v16, v80, v80
	v_fmac_f32_e32 v16, v81, v81
	v_fmac_f32_e32 v16, v82, v82
	v_fmac_f32_e32 v16, v83, v83
	v_fmac_f32_e32 v16, v84, v84
	v_fmac_f32_e32 v16, v85, v85
	v_cvt_f32_f64_e32 v19, v[52:53]
	v_cvt_f32_f64_e32 v53, v[62:63]
	v_add_f32_dpp v16, v16, v16 row_ror:8 row_mask:0xf bank_mask:0xf bound_ctrl:1
	v_sin_f32_e32 v72, v17
	v_cos_f32_e32 v62, v17
	v_add_f32_dpp v16, v16, v16 row_ror:4 row_mask:0xf bank_mask:0xf bound_ctrl:1
	v_sin_f32_e32 v102, v18
	v_cos_f32_e32 v59, v18
	v_add_f32_dpp v16, v16, v16 quad_perm:[2,3,0,1] row_mask:0xf bank_mask:0xf bound_ctrl:1
	v_sin_f32_e32 v73, v19
	v_cos_f32_e32 v63, v19
	v_add_f32_dpp v16, v16, v16 quad_perm:[1,0,3,2] row_mask:0xf bank_mask:0xf bound_ctrl:1
	v_fmamk_f32 v16, v16, 0x3c000000, v205
	v_mul_f32_e32 v17, 0x4f800000, v16
	v_cmp_gt_f32_e32 vcc, s8, v16
	s_waitcnt vmcnt(1)
	v_and_b32_e32 v87, 0xffff0000, v54
	v_lshlrev_b32_e32 v88, 16, v55
	v_cndmask_b32_e32 v16, v16, v17, vcc
	v_sqrt_f32_e32 v17, v16
	v_and_b32_e32 v89, 0xffff0000, v55
	v_lshlrev_b32_e32 v90, 16, v56
	v_and_b32_e32 v91, 0xffff0000, v56
	v_add_u32_e32 v18, -1, v17
	v_fma_f32 v19, -v18, v17, v16
	v_cmp_ge_f32_e64 s[0:1], 0, v19
	v_add_u32_e32 v19, 1, v17
	v_lshlrev_b32_e32 v92, 16, v57
	v_cndmask_b32_e64 v18, v17, v18, s[0:1]
	v_fma_f32 v17, -v19, v17, v16
	v_cmp_lt_f32_e64 s[0:1], 0, v17
	v_and_b32_e32 v93, 0xffff0000, v57
	v_sin_f32_e32 v67, v22
	v_cndmask_b32_e64 v17, v18, v19, s[0:1]
	v_mul_f32_e32 v18, 0x37800000, v17
	v_cndmask_b32_e32 v17, v17, v18, vcc
	v_cmp_class_f32_e32 vcc, v16, v206
	v_cos_f32_e32 v52, v22
	v_sin_f32_e32 v104, v23
	v_cndmask_b32_e32 v94, v17, v16, vcc
	v_div_scale_f32 v96, s[0:1], v94, v94, 1.0
	v_rcp_f32_e32 v97, v96
	v_cos_f32_e32 v60, v23
	global_load_dwordx4 v[98:101], v[76:77], off offset:1024
	global_load_dwordx4 v[20:23], v[76:77], off offset:2048
	global_load_dwordx4 v[16:19], v[76:77], off offset:3072
	v_div_scale_f32 v106, vcc, 1.0, v94, 1.0
	v_fma_f32 v86, -v96, v97, 1.0
	v_fmac_f32_e32 v97, v86, v97
	v_lshlrev_b32_e32 v86, 16, v54
	v_mul_f32_e32 v54, v87, v87
	v_fmac_f32_e32 v54, v86, v86
	v_fmac_f32_e32 v54, v88, v88
	v_fmac_f32_e32 v54, v89, v89
	v_fmac_f32_e32 v54, v90, v90
	v_fmac_f32_e32 v54, v91, v91
	v_fmac_f32_e32 v54, v92, v92
	v_fmac_f32_e32 v54, v93, v93
	v_mul_f32_e32 v56, v106, v97
	v_fma_f32 v57, -v96, v56, v106
	v_add_f32_dpp v54, v54, v54 row_ror:8 row_mask:0xf bank_mask:0xf bound_ctrl:1
	v_fmac_f32_e32 v56, v57, v97
	v_sin_f32_e32 v103, v53
	v_add_f32_dpp v54, v54, v54 row_ror:4 row_mask:0xf bank_mask:0xf bound_ctrl:1
	v_sin_f32_e32 v105, v61
	s_waitcnt vmcnt(3)
; __device__ __forceinline__ unsigned pk2(float lo, float hi) { return f2bf(lo) | (f2bf(hi) << 16); }
; template <int CTRL> __device__ __forceinline__ float dpp_f(float v) { return __builtin_bit_cast(float, __builtin_amdgcn_update_dpp(0, __builtin_bit_cast(int, v), CTRL, 0xF, 0xF, true)); }
; __device__ __forceinline__ float row16_sum(float v) { v += dpp_f<0x128>(v); v += dpp_f<0x124>(v); v += dpp_f<0x4E>(v); v += dpp_f<0xB1>(v); return v; }
; template <int NIT, bool F8>
; __device__ __forceinline__ void post_segment(bf16_t* seg, const float* gain, const float (&cs)[8], const float (&sn)[8], int c, int grp, unsigned char* k8 = nullptr) {
;     const f32x4 g0 = *(const f32x4*)(gain + 8 * c), g1 = *(const f32x4*)(gain + 8 * c + 4);
;     const float g[8] = {g0[0], g0[1], g0[2], g0[3], g1[0], g1[1], g1[2], g1[3]};
;     u32x4 raw[NIT];
; #pragma unroll
;     for (int it = 0; it < NIT; ++it) raw[it] = *(const u32x4*)(seg + (it * 4 + grp) * 128 + c * 8);
; #pragma unroll
;     for (int it = 0; it < NIT; ++it) {
;         const unsigned w[4] = {raw[it].x, raw[it].y, raw[it].z, raw[it].w}; float x[8];
; #pragma unroll
;         for (int i = 0; i < 4; ++i) { x[2 * i] = bf2f(w[i] & 0xffffu); x[2 * i + 1] = __builtin_bit_cast(float, w[i] & 0xffff0000u); }
;         float ss = 0.f;
; #pragma unroll
;         for (int e = 0; e < 8; ++e) ss += x[e] * x[e];
;         ss = row16_sum(ss); const float r = 1.f / sqrtf(ss * (1.f / 128.f) + EPS);
;         float o[8];
; #pragma unroll
;         for (int e = 0; e < 8; ++e) { const float y = x[e] * r * g[e]; const float py = dpp_f<0x128>(y); o[e] = y * cs[e] + py * sn[e]; }
;         u32x4 ow; ow.x = pk2(o[0], o[1]); ow.y = pk2(o[2], o[3]); ow.z = pk2(o[4], o[5]); ow.w = pk2(o[6], o[7]);
;         if constexpr (F8) *(u32x2*)(k8 + (it * 4 + grp) * 128 + c * 8) = to_fp8x8(o);
;         else *(u32x4*)(seg + (it * 4 + grp) * 128 + c * 8) = ow;
;     }
	v_lshlrev_b32_e32 v108, 16, v70
	v_add_f32_dpp v54, v54, v54 quad_perm:[2,3,0,1] row_mask:0xf bank_mask:0xf bound_ctrl:1
	v_and_b32_e32 v110, 0xffff0000, v70
	v_lshlrev_b32_e32 v109, 16, v71
	v_add_f32_dpp v54, v54, v54 quad_perm:[1,0,3,2] row_mask:0xf bank_mask:0xf bound_ctrl:1
	v_fmamk_f32 v54, v54, 0x3c000000, v205
	v_mul_f32_e32 v55, 0x4f800000, v54
	v_cmp_gt_f32_e64 s[0:1], s8, v54
	v_and_b32_e32 v111, 0xffff0000, v71
	v_mov_b32_e32 v70, v110
	v_cndmask_b32_e64 v54, v54, v55, s[0:1]
	v_sqrt_f32_e32 v55, v54
	v_mov_b32_e32 v71, v108
	v_pk_mul_f32 v[70:71], v[70:71], v[70:71]
	v_mov_b32_e32 v112, v111
	v_add_u32_e32 v57, -1, v55
	v_fma_f32 v95, -v57, v55, v54
	v_cmp_ge_f32_e64 s[40:41], 0, v95
	v_add_u32_e32 v95, 1, v55
	v_mov_b32_e32 v113, v109
	v_cndmask_b32_e64 v57, v55, v57, s[40:41]
	v_fma_f32 v55, -v95, v55, v54
	v_cmp_lt_f32_e64 s[40:41], 0, v55
	v_pk_mul_f32 v[112:113], v[112:113], v[112:113]
	v_cos_f32_e32 v61, v61
	v_cndmask_b32_e64 v55, v57, v95, s[40:41]
	v_mul_f32_e32 v57, 0x37800000, v55
	v_cndmask_b32_e64 v55, v55, v57, s[0:1]
	v_cmp_class_f32_e64 s[0:1], v54, v206
	v_fma_f32 v57, -v96, v56, v106
	v_div_fmas_f32 v97, v57, v97, v56
	v_cndmask_b32_e64 v95, v55, v54, s[0:1]
	v_div_scale_f32 v54, s[0:1], v95, v95, 1.0
	v_rcp_f32_e32 v55, v54
	v_cos_f32_e32 v53, v53
	v_fma_f32 v56, -v54, v55, 1.0
	v_fmac_f32_e32 v55, v56, v55
	v_div_scale_f32 v56, vcc, 1.0, v95, 1.0
	v_mul_f32_e32 v57, v56, v55
	v_fma_f32 v96, -v54, v57, v56
	v_fmac_f32_e32 v57, v96, v55
	v_fma_f32 v54, -v54, v57, v56
	v_div_fmas_f32 v96, v54, v55, v57
	v_pk_mul_f32 v[54:55], v[34:35], v[66:67]
	v_pk_mul_f32 v[56:57], v[34:35], v[102:103]
	v_pk_mul_f32 v[66:67], v[34:35], v[72:73]
	v_lshlrev_b32_e32 v73, 16, v69
	v_lshlrev_b32_e32 v72, 16, v68
	v_and_b32_e32 v103, 0xffff0000, v69
	v_and_b32_e32 v102, 0xffff0000, v68
	v_pk_mul_f32 v[68:69], v[72:73], v[72:73]
	v_pk_mul_f32 v[106:107], v[102:103], v[102:103]
	s_nop 0
	v_add_f32_e32 v68, v68, v106
	v_add_f32_e32 v68, v69, v68
	v_add_f32_e32 v68, v107, v68
	v_add_f32_e32 v68, v71, v68
	v_add_f32_e32 v68, v70, v68
	v_add_f32_e32 v68, v113, v68
	v_add_f32_e32 v68, v112, v68
	v_mov_b32_e32 v106, v12
	v_mov_b32_e32 v107, v14
	v_add_f32_dpp v68, v68, v68 row_ror:8 row_mask:0xf bank_mask:0xf bound_ctrl:1
	v_mov_b32_e32 v14, v13
	v_mov_b32_e32 v70, v54
	v_add_f32_dpp v68, v68, v68 row_ror:4 row_mask:0xf bank_mask:0xf bound_ctrl:1
	v_mov_b32_e32 v71, v56
	s_nop 0
	v_add_f32_dpp v68, v68, v68 quad_perm:[2,3,0,1] row_mask:0xf bank_mask:0xf bound_ctrl:1
	s_nop 1
	v_add_f32_dpp v68, v68, v68 quad_perm:[1,0,3,2] row_mask:0xf bank_mask:0xf bound_ctrl:1
	v_fmamk_f32 v68, v68, 0x3c000000, v205
	s_nop 1
	v_rsq_f32_e32 v12, v68
	v_pk_mul_f32 v[68:69], v[34:35], v[104:105]
	v_pk_mul_f32 v[102:103], v[12:13], v[102:103] op_sel_hi:[0,1]
	v_pk_mul_f32 v[102:103], v[14:15], v[102:103]
	v_pk_mul_f32 v[72:73], v[12:13], v[72:73] op_sel_hi:[0,1]
	v_pk_mul_f32 v[108:109], v[12:13], v[108:109] op_sel_hi:[0,1]
	v_mov_b32_dpp v112, v102 row_ror:8 row_mask:0xf bank_mask:0xf bound_ctrl:1
	v_mov_b32_dpp v113, v103 row_ror:8 row_mask:0xf bank_mask:0xf bound_ctrl:1
	v_pk_mul_f32 v[102:103], v[62:63], v[102:103]
	v_pk_mul_f32 v[12:13], v[12:13], v[110:111] op_sel_hi:[0,1]
	v_pk_fma_f32 v[102:103], v[66:67], v[112:113], v[102:103]
	v_mov_b32_e32 v113, v10
	v_mov_b32_e32 v10, v9
	v_pk_mul_f32 v[72:73], v[106:107], v[72:73]
	v_mov_b32_e32 v112, v8
	v_pk_mul_f32 v[12:13], v[10:11], v[12:13]
	v_mov_b32_dpp v104, v72 row_ror:8 row_mask:0xf bank_mask:0xf bound_ctrl:1
	v_mov_b32_dpp v105, v73 row_ror:8 row_mask:0xf bank_mask:0xf bound_ctrl:1
	v_pk_mul_f32 v[72:73], v[58:59], v[72:73]
	v_pk_mul_f32 v[108:109], v[112:113], v[108:109]
	v_mov_b32_dpp v110, v12 row_ror:8 row_mask:0xf bank_mask:0xf bound_ctrl:1
	v_mov_b32_dpp v111, v13 row_ror:8 row_mask:0xf bank_mask:0xf bound_ctrl:1
	v_pk_mul_f32 v[12:13], v[60:61], v[12:13]
	v_mov_b32_dpp v8, v108 row_ror:8 row_mask:0xf bank_mask:0xf bound_ctrl:1
	v_mov_b32_dpp v9, v109 row_ror:8 row_mask:0xf bank_mask:0xf bound_ctrl:1
	v_pk_mul_f32 v[108:109], v[52:53], v[108:109]
	v_pk_fma_f32 v[12:13], v[68:69], v[110:111], v[12:13]
	v_pk_fma_f32 v[104:105], v[70:71], v[104:105], v[72:73]
	v_mov_b32_e32 v72, v55
	v_mov_b32_e32 v73, v57
	v_pk_fma_f32 v[8:9], v[72:73], v[8:9], v[108:109]
	v_bfe_u32 v108, v13, 16, 1
	v_bfe_u32 v109, v12, 16, 1
	v_bfe_u32 v110, v103, 16, 1
	v_bfe_u32 v111, v102, 16, 1
	v_add3_u32 v114, v102, v111, s33
	v_add3_u32 v115, v103, v110, s33
	v_add3_u32 v116, v12, v109, s33
	v_add3_u32 v117, v13, v108, s33
	v_bfe_u32 v12, v104, 16, 1
	v_bfe_u32 v13, v105, 16, 1
	v_bfe_u32 v102, v8, 16, 1
	v_bfe_u32 v103, v9, 16, 1
	v_add3_u32 v118, v9, v103, s33
	v_add3_u32 v8, v8, v102, s33
	v_add3_u32 v9, v105, v13, s33
	v_add3_u32 v12, v104, v12, s33
	v_lshrrev_b32_e32 v119, 16, v12
	v_lshrrev_b32_e32 v120, 16, v9
	v_lshrrev_b32_e32 v121, 16, v8
	s_waitcnt vmcnt(2)
; __device__ __forceinline__ unsigned pk2(float lo, float hi) { return f2bf(lo) | (f2bf(hi) << 16); }
; template <int CTRL> __device__ __forceinline__ float dpp_f(float v) { return __builtin_bit_cast(float, __builtin_amdgcn_update_dpp(0, __builtin_bit_cast(int, v), CTRL, 0xF, 0xF, true)); }
; __device__ __forceinline__ float row16_sum(float v) { v += dpp_f<0x128>(v); v += dpp_f<0x124>(v); v += dpp_f<0x4E>(v); v += dpp_f<0xB1>(v); return v; }
; template <int NIT, bool F8>
; __device__ __forceinline__ void post_segment(bf16_t* seg, const float* gain, const float (&cs)[8], const float (&sn)[8], int c, int grp, unsigned char* k8 = nullptr) {
;     const f32x4 g0 = *(const f32x4*)(gain + 8 * c), g1 = *(const f32x4*)(gain + 8 * c + 4);
;     const float g[8] = {g0[0], g0[1], g0[2], g0[3], g1[0], g1[1], g1[2], g1[3]};
;     u32x4 raw[NIT];
; #pragma unroll
;     for (int it = 0; it < NIT; ++it) raw[it] = *(const u32x4*)(seg + (it * 4 + grp) * 128 + c * 8);
; #pragma unroll
;     for (int it = 0; it < NIT; ++it) {
;         const unsigned w[4] = {raw[it].x, raw[it].y, raw[it].z, raw[it].w}; float x[8];
; #pragma unroll
;         for (int i = 0; i < 4; ++i) { x[2 * i] = bf2f(w[i] & 0xffffu); x[2 * i + 1] = __builtin_bit_cast(float, w[i] & 0xffff0000u); }
;         float ss = 0.f;
; #pragma unroll
;         for (int e = 0; e < 8; ++e) ss += x[e] * x[e];
;         ss = row16_sum(ss); const float r = 1.f / sqrtf(ss * (1.f / 128.f) + EPS);
;         float o[8];
; #pragma unroll
;         for (int e = 0; e < 8; ++e) { const float y = x[e] * r * g[e]; const float py = dpp_f<0x128>(y); o[e] = y * cs[e] + py * sn[e]; }
;         u32x4 ow; ow.x = pk2(o[0], o[1]); ow.y = pk2(o[2], o[3]); ow.z = pk2(o[4], o[5]); ow.w = pk2(o[6], o[7]);
;         if constexpr (F8) *(u32x2*)(k8 + (it * 4 + grp) * 128 + c * 8) = to_fp8x8(o);
;         else *(u32x4*)(seg + (it * 4 + grp) * 128 + c * 8) = ow;
;     }
	v_lshlrev_b32_e32 v9, 16, v99
	v_lshlrev_b32_e32 v8, 16, v98
	v_and_b32_e32 v13, 0xffff0000, v99
	v_and_b32_e32 v12, 0xffff0000, v98
	v_pk_mul_f32 v[98:99], v[8:9], v[8:9]
	v_pk_mul_f32 v[102:103], v[12:13], v[12:13]
	v_lshlrev_b32_e32 v104, 16, v100
	v_and_b32_e32 v108, 0xffff0000, v100
	v_add_f32_e32 v98, v98, v102
	v_lshlrev_b32_e32 v105, 16, v101
	v_and_b32_e32 v109, 0xffff0000, v101
	v_mov_b32_e32 v100, v108
	v_mov_b32_e32 v101, v104
	v_add_f32_e32 v98, v99, v98
	v_pk_mul_f32 v[100:101], v[100:101], v[100:101]
	v_add_f32_e32 v98, v103, v98
	v_mov_b32_e32 v110, v109
	v_mov_b32_e32 v111, v105
	v_add_f32_e32 v98, v101, v98
	v_pk_mul_f32 v[110:111], v[110:111], v[110:111]
	v_add_f32_e32 v98, v100, v98
	v_add_f32_e32 v98, v111, v98
	v_add_f32_e32 v98, v110, v98
	v_lshrrev_b32_e32 v100, 16, v118
	v_and_or_b32 v101, v117, s67, v100
	v_add_f32_dpp v98, v98, v98 row_ror:8 row_mask:0xf bank_mask:0xf bound_ctrl:1
	v_and_or_b32 v100, v116, s67, v121
	s_nop 0
	v_add_f32_dpp v98, v98, v98 row_ror:4 row_mask:0xf bank_mask:0xf bound_ctrl:1
	s_nop 1
	v_add_f32_dpp v98, v98, v98 quad_perm:[2,3,0,1] row_mask:0xf bank_mask:0xf bound_ctrl:1
	s_nop 1
	v_add_f32_dpp v98, v98, v98 quad_perm:[1,0,3,2] row_mask:0xf bank_mask:0xf bound_ctrl:1
	v_fmamk_f32 v98, v98, 0x3c000000, v205
	s_nop 1
	v_rsq_f32_e32 v102, v98
	v_and_or_b32 v99, v115, s67, v120
	v_and_or_b32 v98, v114, s67, v119
	global_store_dwordx4 v[74:75], v[98:101], off offset:-4096
	s_nop 1
	v_mov_b32_e32 v98, v102
	v_pk_mul_f32 v[8:9], v[98:99], v[8:9] op_sel_hi:[0,1]
	v_pk_mul_f32 v[12:13], v[98:99], v[12:13] op_sel_hi:[0,1]
	v_pk_mul_f32 v[104:105], v[98:99], v[104:105] op_sel_hi:[0,1]
	v_pk_mul_f32 v[98:99], v[98:99], v[108:109] op_sel_hi:[0,1]
	v_pk_mul_f32 v[12:13], v[14:15], v[12:13]
	v_pk_mul_f32 v[98:99], v[10:11], v[98:99]
	v_pk_mul_f32 v[8:9], v[106:107], v[8:9]
	v_mov_b32_dpp v102, v12 row_ror:8 row_mask:0xf bank_mask:0xf bound_ctrl:1
	v_mov_b32_dpp v103, v13 row_ror:8 row_mask:0xf bank_mask:0xf bound_ctrl:1
	v_pk_mul_f32 v[12:13], v[62:63], v[12:13]
	v_pk_mul_f32 v[104:105], v[112:113], v[104:105]
	v_mov_b32_dpp v108, v98 row_ror:8 row_mask:0xf bank_mask:0xf bound_ctrl:1
	v_mov_b32_dpp v109, v99 row_ror:8 row_mask:0xf bank_mask:0xf bound_ctrl:1
	v_mov_b32_dpp v100, v8 row_ror:8 row_mask:0xf bank_mask:0xf bound_ctrl:1
	v_mov_b32_dpp v101, v9 row_ror:8 row_mask:0xf bank_mask:0xf bound_ctrl:1
	v_pk_mul_f32 v[8:9], v[58:59], v[8:9]
	v_mov_b32_dpp v110, v104 row_ror:8 row_mask:0xf bank_mask:0xf bound_ctrl:1
	v_mov_b32_dpp v111, v105 row_ror:8 row_mask:0xf bank_mask:0xf bound_ctrl:1
	v_pk_fma_f32 v[12:13], v[66:67], v[102:103], v[12:13]
	v_pk_mul_f32 v[102:103], v[68:69], v[108:109]
	v_pk_fma_f32 v[8:9], v[70:71], v[100:101], v[8:9]
	v_pk_fma_f32 v[98:99], v[60:61], v[98:99], v[102:103]
	v_pk_mul_f32 v[100:101], v[72:73], v[110:111]
	v_bfe_u32 v102, v13, 16, 1
	v_pk_fma_f32 v[100:101], v[52:53], v[104:105], v[100:101]
	v_bfe_u32 v103, v12, 16, 1
	v_bfe_u32 v104, v99, 16, 1
	v_bfe_u32 v105, v98, 16, 1
	v_add3_u32 v108, v98, v105, s33
	v_add3_u32 v109, v99, v104, s33
	v_add3_u32 v110, v12, v103, s33
	v_add3_u32 v111, v13, v102, s33
	v_bfe_u32 v12, v100, 16, 1
	v_bfe_u32 v13, v101, 16, 1
	v_bfe_u32 v98, v8, 16, 1
	v_bfe_u32 v99, v9, 16, 1
	v_add3_u32 v114, v9, v99, s33
	v_add3_u32 v8, v8, v98, s33
	v_add3_u32 v9, v101, v13, s33
	v_add3_u32 v12, v100, v12, s33
	v_lshrrev_b32_e32 v115, 16, v12
	v_lshrrev_b32_e32 v116, 16, v9
	v_lshrrev_b32_e32 v117, 16, v8
	s_waitcnt vmcnt(2)
	v_lshlrev_b32_e32 v9, 16, v21
	v_lshlrev_b32_e32 v8, 16, v20
	v_and_b32_e32 v13, 0xffff0000, v21
	v_and_b32_e32 v12, 0xffff0000, v20
	v_pk_mul_f32 v[20:21], v[8:9], v[8:9]
	v_pk_mul_f32 v[98:99], v[12:13], v[12:13]
	v_lshlrev_b32_e32 v100, 16, v22
	v_and_b32_e32 v102, 0xffff0000, v22
	v_add_f32_e32 v20, v20, v98
	v_lshlrev_b32_e32 v101, 16, v23
	v_and_b32_e32 v103, 0xffff0000, v23
	v_mov_b32_e32 v22, v102
	v_mov_b32_e32 v23, v100
	v_add_f32_e32 v20, v21, v20
	v_pk_mul_f32 v[22:23], v[22:23], v[22:23]
	v_add_f32_e32 v20, v99, v20
	v_mov_b32_e32 v104, v103
	v_mov_b32_e32 v105, v101
	v_add_f32_e32 v20, v23, v20
	v_pk_mul_f32 v[104:105], v[104:105], v[104:105]
	v_add_f32_e32 v20, v22, v20
	v_add_f32_e32 v20, v105, v20
	v_add_f32_e32 v20, v104, v20
	s_waitcnt vmcnt(1)
; __device__ __forceinline__ unsigned pk2(float lo, float hi) { return f2bf(lo) | (f2bf(hi) << 16); }
; template <int CTRL> __device__ __forceinline__ float dpp_f(float v) { return __builtin_bit_cast(float, __builtin_amdgcn_update_dpp(0, __builtin_bit_cast(int, v), CTRL, 0xF, 0xF, true)); }
; __device__ __forceinline__ float row16_sum(float v) { v += dpp_f<0x128>(v); v += dpp_f<0x124>(v); v += dpp_f<0x4E>(v); v += dpp_f<0xB1>(v); return v; }
; template <int NIT, bool F8>
; __device__ __forceinline__ void post_segment(bf16_t* seg, const float* gain, const float (&cs)[8], const float (&sn)[8], int c, int grp, unsigned char* k8 = nullptr) {
;     const f32x4 g0 = *(const f32x4*)(gain + 8 * c), g1 = *(const f32x4*)(gain + 8 * c + 4);
;     const float g[8] = {g0[0], g0[1], g0[2], g0[3], g1[0], g1[1], g1[2], g1[3]};
;     u32x4 raw[NIT];
; #pragma unroll
;     for (int it = 0; it < NIT; ++it) raw[it] = *(const u32x4*)(seg + (it * 4 + grp) * 128 + c * 8);
; #pragma unroll
;     for (int it = 0; it < NIT; ++it) {
;         const unsigned w[4] = {raw[it].x, raw[it].y, raw[it].z, raw[it].w}; float x[8];
; #pragma unroll
;         for (int i = 0; i < 4; ++i) { x[2 * i] = bf2f(w[i] & 0xffffu); x[2 * i + 1] = __builtin_bit_cast(float, w[i] & 0xffff0000u); }
;         float ss = 0.f;
; #pragma unroll
;         for (int e = 0; e < 8; ++e) ss += x[e] * x[e];
;         ss = row16_sum(ss); const float r = 1.f / sqrtf(ss * (1.f / 128.f) + EPS);
;         float o[8];
; #pragma unroll
;         for (int e = 0; e < 8; ++e) { const float y = x[e] * r * g[e]; const float py = dpp_f<0x128>(y); o[e] = y * cs[e] + py * sn[e]; }
;         u32x4 ow; ow.x = pk2(o[0], o[1]); ow.y = pk2(o[2], o[3]); ow.z = pk2(o[4], o[5]); ow.w = pk2(o[6], o[7]);
;         if constexpr (F8) *(u32x2*)(k8 + (it * 4 + grp) * 128 + c * 8) = to_fp8x8(o);
;         else *(u32x4*)(seg + (it * 4 + grp) * 128 + c * 8) = ow;
;     }
	v_and_b32_e32 v105, 0xffff0000, v17
	v_add_f32_dpp v20, v20, v20 row_ror:8 row_mask:0xf bank_mask:0xf bound_ctrl:1
	s_nop 1
	v_add_f32_dpp v20, v20, v20 row_ror:4 row_mask:0xf bank_mask:0xf bound_ctrl:1
	s_nop 1
	v_add_f32_dpp v20, v20, v20 quad_perm:[2,3,0,1] row_mask:0xf bank_mask:0xf bound_ctrl:1
	s_nop 1
	v_add_f32_dpp v20, v20, v20 quad_perm:[1,0,3,2] row_mask:0xf bank_mask:0xf bound_ctrl:1
	v_fmamk_f32 v20, v20, 0x3c000000, v205
	s_nop 1
	v_rsq_f32_e32 v98, v20
	v_lshrrev_b32_e32 v20, 16, v114
	v_and_or_b32 v21, v111, s67, v20
	v_and_or_b32 v20, v110, s67, v117
	v_and_or_b32 v23, v109, s67, v116
	v_and_or_b32 v22, v108, s67, v115
	global_store_dwordx4 v[76:77], v[20:23], off offset:1024
	v_and_b32_e32 v108, 0xffff0000, v18
	v_and_b32_e32 v109, 0xffff0000, v19
	v_mov_b32_e32 v20, v98
	v_pk_mul_f32 v[8:9], v[20:21], v[8:9] op_sel_hi:[0,1]
	v_pk_mul_f32 v[12:13], v[20:21], v[12:13] op_sel_hi:[0,1]
	v_pk_mul_f32 v[98:99], v[20:21], v[100:101] op_sel_hi:[0,1]
	v_pk_mul_f32 v[20:21], v[20:21], v[102:103] op_sel_hi:[0,1]
	v_pk_mul_f32 v[12:13], v[14:15], v[12:13]
	v_pk_mul_f32 v[10:11], v[10:11], v[20:21]
	v_pk_mul_f32 v[98:99], v[112:113], v[98:99]
	v_mov_b32_dpp v14, v12 row_ror:8 row_mask:0xf bank_mask:0xf bound_ctrl:1
	v_mov_b32_dpp v15, v13 row_ror:8 row_mask:0xf bank_mask:0xf bound_ctrl:1
	v_pk_mul_f32 v[12:13], v[62:63], v[12:13]
	v_mov_b32_dpp v20, v10 row_ror:8 row_mask:0xf bank_mask:0xf bound_ctrl:1
	v_mov_b32_dpp v21, v11 row_ror:8 row_mask:0xf bank_mask:0xf bound_ctrl:1
	v_pk_mul_f32 v[8:9], v[106:107], v[8:9]
	v_mov_b32_dpp v100, v98 row_ror:8 row_mask:0xf bank_mask:0xf bound_ctrl:1
	v_mov_b32_dpp v101, v99 row_ror:8 row_mask:0xf bank_mask:0xf bound_ctrl:1
	v_pk_fma_f32 v[12:13], v[66:67], v[14:15], v[12:13]
	v_pk_mul_f32 v[14:15], v[68:69], v[20:21]
	v_mov_b32_dpp v22, v8 row_ror:8 row_mask:0xf bank_mask:0xf bound_ctrl:1
	v_mov_b32_dpp v23, v9 row_ror:8 row_mask:0xf bank_mask:0xf bound_ctrl:1
	v_pk_mul_f32 v[8:9], v[58:59], v[8:9]
	v_pk_fma_f32 v[10:11], v[60:61], v[10:11], v[14:15]
	v_pk_mul_f32 v[14:15], v[72:73], v[100:101]
	v_pk_fma_f32 v[8:9], v[70:71], v[22:23], v[8:9]
	v_pk_fma_f32 v[14:15], v[52:53], v[98:99], v[14:15]
	v_cvt_pk_bf16_f32 v9, v9, v13
	v_cvt_pk_bf16_f32 v8, v8, v12
	v_cvt_pk_bf16_f32 v11, v15, v11
	v_cvt_pk_bf16_f32 v10, v14, v10
	global_store_dwordx4 v[76:77], v[8:11], off offset:2048
	global_load_dwordx4 v[20:23], v[26:27], off
	global_load_dwordx4 v[12:15], v[26:27], off offset:16
	global_load_dwordx4 v[98:101], v[74:75], off
	v_lshlrev_b32_e32 v103, 16, v17
	v_lshlrev_b32_e32 v102, 16, v16
	v_and_b32_e32 v104, 0xffff0000, v16
	v_pk_mul_f32 v[8:9], v[102:103], v[102:103]
	v_pk_mul_f32 v[10:11], v[104:105], v[104:105]
	v_lshlrev_b32_e32 v106, 16, v18
	v_add_f32_e32 v8, v8, v10
	v_mov_b32_e32 v16, v108
	v_mov_b32_e32 v17, v106
	v_add_f32_e32 v8, v9, v8
	v_lshlrev_b32_e32 v107, 16, v19
	v_pk_mul_f32 v[16:17], v[16:17], v[16:17]
	v_add_f32_e32 v8, v11, v8
	v_mov_b32_e32 v18, v109
	v_mov_b32_e32 v19, v107
	v_add_f32_e32 v8, v17, v8
	v_pk_mul_f32 v[18:19], v[18:19], v[18:19]
	v_add_f32_e32 v8, v16, v8
	v_add_f32_e32 v8, v19, v8
	v_add_f32_e32 v8, v18, v8
	s_nop 1
	v_add_f32_dpp v8, v8, v8 row_ror:8 row_mask:0xf bank_mask:0xf bound_ctrl:1
	s_nop 1
	v_add_f32_dpp v8, v8, v8 row_ror:4 row_mask:0xf bank_mask:0xf bound_ctrl:1
	s_nop 1
	v_add_f32_dpp v8, v8, v8 quad_perm:[2,3,0,1] row_mask:0xf bank_mask:0xf bound_ctrl:1
	s_nop 1
	v_add_f32_dpp v8, v8, v8 quad_perm:[1,0,3,2] row_mask:0xf bank_mask:0xf bound_ctrl:1
	v_fmamk_f32 v8, v8, 0x3c000000, v205
	s_nop 1
	v_rsq_f32_e32 v112, v8
	global_load_dwordx4 v[8:11], v[64:65], off offset:1024
	global_load_dwordx4 v[16:19], v[74:75], off offset:1024
	s_waitcnt vmcnt(4)
	v_mov_b32_e32 v110, v20
	v_mov_b32_e32 v111, v22
	v_mov_b32_e32 v22, v21
	v_mov_b32_e32 v20, v112
	v_pk_mul_f32 v[102:103], v[20:21], v[102:103] op_sel_hi:[0,1]
	v_pk_mul_f32 v[102:103], v[110:111], v[102:103]
	v_pk_mul_f32 v[104:105], v[20:21], v[104:105] op_sel_hi:[0,1]
	v_pk_mul_f32 v[106:107], v[20:21], v[106:107] op_sel_hi:[0,1]
	v_pk_mul_f32 v[20:21], v[20:21], v[108:109] op_sel_hi:[0,1]
	v_mov_b32_dpp v108, v102 row_ror:8 row_mask:0xf bank_mask:0xf bound_ctrl:1
	v_mov_b32_dpp v109, v103 row_ror:8 row_mask:0xf bank_mask:0xf bound_ctrl:1
	v_pk_mul_f32 v[102:103], v[58:59], v[102:103]
	v_pk_mul_f32 v[104:105], v[22:23], v[104:105]
	v_pk_fma_f32 v[102:103], v[70:71], v[108:109], v[102:103]
	s_waitcnt vmcnt(3)
	v_mov_b32_e32 v109, v14
	v_mov_b32_e32 v14, v13
	v_mov_b32_dpp v112, v104 row_ror:8 row_mask:0xf bank_mask:0xf bound_ctrl:1
	v_mov_b32_dpp v113, v105 row_ror:8 row_mask:0xf bank_mask:0xf bound_ctrl:1
	v_pk_mul_f32 v[104:105], v[62:63], v[104:105]
	v_mov_b32_e32 v108, v12
	v_pk_mul_f32 v[20:21], v[14:15], v[20:21]
	v_pk_fma_f32 v[104:105], v[66:67], v[112:113], v[104:105]
	v_pk_mul_f32 v[106:107], v[108:109], v[106:107]
	v_mov_b32_dpp v112, v20 row_ror:8 row_mask:0xf bank_mask:0xf bound_ctrl:1
	v_mov_b32_dpp v113, v21 row_ror:8 row_mask:0xf bank_mask:0xf bound_ctrl:1
	v_pk_mul_f32 v[20:21], v[60:61], v[20:21]
	v_mov_b32_dpp v12, v106 row_ror:8 row_mask:0xf bank_mask:0xf bound_ctrl:1
	v_mov_b32_dpp v13, v107 row_ror:8 row_mask:0xf bank_mask:0xf bound_ctrl:1
	v_pk_mul_f32 v[106:107], v[52:53], v[106:107]
	v_pk_fma_f32 v[20:21], v[68:69], v[112:113], v[20:21]
	v_pk_fma_f32 v[12:13], v[72:73], v[12:13], v[106:107]
	v_bfe_u32 v106, v21, 16, 1
	v_bfe_u32 v107, v20, 16, 1
	v_bfe_u32 v112, v105, 16, 1
	v_bfe_u32 v113, v104, 16, 1
	v_add3_u32 v114, v104, v113, s33
	v_add3_u32 v115, v105, v112, s33
	v_add3_u32 v116, v20, v107, s33
	v_add3_u32 v117, v21, v106, s33
	v_bfe_u32 v20, v102, 16, 1
	v_bfe_u32 v21, v103, 16, 1
	v_bfe_u32 v104, v12, 16, 1
	v_bfe_u32 v105, v13, 16, 1
	v_add3_u32 v118, v13, v105, s33
	v_add3_u32 v12, v12, v104, s33
	v_add3_u32 v13, v103, v21, s33
	v_add3_u32 v20, v102, v20, s33
	v_lshrrev_b32_e32 v119, 16, v20
	v_lshrrev_b32_e32 v120, 16, v13
	v_lshrrev_b32_e32 v121, 16, v12
	s_waitcnt vmcnt(2)
; __device__ __forceinline__ unsigned pk2(float lo, float hi) { return f2bf(lo) | (f2bf(hi) << 16); }
; template <int CTRL> __device__ __forceinline__ float dpp_f(float v) { return __builtin_bit_cast(float, __builtin_amdgcn_update_dpp(0, __builtin_bit_cast(int, v), CTRL, 0xF, 0xF, true)); }
; __device__ __forceinline__ float row16_sum(float v) { v += dpp_f<0x128>(v); v += dpp_f<0x124>(v); v += dpp_f<0x4E>(v); v += dpp_f<0xB1>(v); return v; }
; template <int NIT, bool F8>
; __device__ __forceinline__ void post_segment(bf16_t* seg, const float* gain, const float (&cs)[8], const float (&sn)[8], int c, int grp, unsigned char* k8 = nullptr) {
;     const f32x4 g0 = *(const f32x4*)(gain + 8 * c), g1 = *(const f32x4*)(gain + 8 * c + 4);
;     const float g[8] = {g0[0], g0[1], g0[2], g0[3], g1[0], g1[1], g1[2], g1[3]};
;     u32x4 raw[NIT];
; #pragma unroll
;     for (int it = 0; it < NIT; ++it) raw[it] = *(const u32x4*)(seg + (it * 4 + grp) * 128 + c * 8);
; #pragma unroll
;     for (int it = 0; it < NIT; ++it) {
;         const unsigned w[4] = {raw[it].x, raw[it].y, raw[it].z, raw[it].w}; float x[8];
; #pragma unroll
;         for (int i = 0; i < 4; ++i) { x[2 * i] = bf2f(w[i] & 0xffffu); x[2 * i + 1] = __builtin_bit_cast(float, w[i] & 0xffff0000u); }
;         float ss = 0.f;
; #pragma unroll
;         for (int e = 0; e < 8; ++e) ss += x[e] * x[e];
;         ss = row16_sum(ss); const float r = 1.f / sqrtf(ss * (1.f / 128.f) + EPS);
;         float o[8];
; #pragma unroll
;         for (int e = 0; e < 8; ++e) { const float y = x[e] * r * g[e]; const float py = dpp_f<0x128>(y); o[e] = y * cs[e] + py * sn[e]; }
;         u32x4 ow; ow.x = pk2(o[0], o[1]); ow.y = pk2(o[2], o[3]); ow.z = pk2(o[4], o[5]); ow.w = pk2(o[6], o[7]);
;         if constexpr (F8) *(u32x2*)(k8 + (it * 4 + grp) * 128 + c * 8) = to_fp8x8(o);
;         else *(u32x4*)(seg + (it * 4 + grp) * 128 + c * 8) = ow;
;     }
	v_lshlrev_b32_e32 v13, 16, v99
	v_lshlrev_b32_e32 v12, 16, v98
	v_and_b32_e32 v21, 0xffff0000, v99
	v_and_b32_e32 v20, 0xffff0000, v98
	v_pk_mul_f32 v[98:99], v[12:13], v[12:13]
	v_pk_mul_f32 v[102:103], v[20:21], v[20:21]
	v_lshlrev_b32_e32 v104, 16, v100
	v_and_b32_e32 v106, 0xffff0000, v100
	v_add_f32_e32 v98, v98, v102
	v_lshlrev_b32_e32 v105, 16, v101
	v_and_b32_e32 v107, 0xffff0000, v101
	v_mov_b32_e32 v100, v106
	v_mov_b32_e32 v101, v104
	v_add_f32_e32 v98, v99, v98
	v_pk_mul_f32 v[100:101], v[100:101], v[100:101]
	v_add_f32_e32 v98, v103, v98
	v_mov_b32_e32 v112, v107
	v_mov_b32_e32 v113, v105
	v_add_f32_e32 v98, v101, v98
	v_pk_mul_f32 v[112:113], v[112:113], v[112:113]
	v_add_f32_e32 v98, v100, v98
	v_add_f32_e32 v98, v113, v98
	v_add_f32_e32 v98, v112, v98
	v_lshrrev_b32_e32 v100, 16, v118
	v_and_or_b32 v101, v117, s67, v100
	v_add_f32_dpp v98, v98, v98 row_ror:8 row_mask:0xf bank_mask:0xf bound_ctrl:1
	v_and_or_b32 v100, v116, s67, v121
	s_nop 0
	v_add_f32_dpp v98, v98, v98 row_ror:4 row_mask:0xf bank_mask:0xf bound_ctrl:1
	s_nop 1
	v_add_f32_dpp v98, v98, v98 quad_perm:[2,3,0,1] row_mask:0xf bank_mask:0xf bound_ctrl:1
	s_nop 1
	v_add_f32_dpp v98, v98, v98 quad_perm:[1,0,3,2] row_mask:0xf bank_mask:0xf bound_ctrl:1
	v_fmamk_f32 v98, v98, 0x3c000000, v205
	s_nop 1
	v_rsq_f32_e32 v102, v98
	v_and_or_b32 v99, v115, s67, v120
	v_and_or_b32 v98, v114, s67, v119
	global_store_dwordx4 v[76:77], v[98:101], off offset:3072
	v_mov_b32_e32 v76, v102
	v_pk_mul_f32 v[12:13], v[76:77], v[12:13] op_sel_hi:[0,1]
	v_pk_mul_f32 v[20:21], v[76:77], v[20:21] op_sel_hi:[0,1]
	v_pk_mul_f32 v[98:99], v[76:77], v[104:105] op_sel_hi:[0,1]
	v_pk_mul_f32 v[12:13], v[110:111], v[12:13]
	v_pk_mul_f32 v[76:77], v[76:77], v[106:107] op_sel_hi:[0,1]
	v_pk_mul_f32 v[20:21], v[22:23], v[20:21]
	v_mov_b32_dpp v100, v12 row_ror:8 row_mask:0xf bank_mask:0xf bound_ctrl:1
	v_mov_b32_dpp v101, v13 row_ror:8 row_mask:0xf bank_mask:0xf bound_ctrl:1
	v_pk_mul_f32 v[12:13], v[58:59], v[12:13]
	v_pk_mul_f32 v[98:99], v[108:109], v[98:99]
	v_mov_b32_dpp v102, v20 row_ror:8 row_mask:0xf bank_mask:0xf bound_ctrl:1
	v_pk_fma_f32 v[12:13], v[70:71], v[100:101], v[12:13]
	v_mov_b32_dpp v103, v21 row_ror:8 row_mask:0xf bank_mask:0xf bound_ctrl:1
	v_pk_mul_f32 v[20:21], v[62:63], v[20:21]
	v_mov_b32_dpp v100, v98 row_ror:8 row_mask:0xf bank_mask:0xf bound_ctrl:1
	v_pk_mul_f32 v[76:77], v[14:15], v[76:77]
	v_mov_b32_dpp v101, v99 row_ror:8 row_mask:0xf bank_mask:0xf bound_ctrl:1
	v_pk_fma_f32 v[20:21], v[66:67], v[102:103], v[20:21]
	v_mov_b32_dpp v102, v76 row_ror:8 row_mask:0xf bank_mask:0xf bound_ctrl:1
	v_pk_mul_f32 v[100:101], v[72:73], v[100:101]
	v_mov_b32_dpp v103, v77 row_ror:8 row_mask:0xf bank_mask:0xf bound_ctrl:1
	v_pk_fma_f32 v[98:99], v[52:53], v[98:99], v[100:101]
	v_pk_mul_f32 v[100:101], v[68:69], v[102:103]
	s_nop 0
	v_pk_fma_f32 v[76:77], v[60:61], v[76:77], v[100:101]
	v_bfe_u32 v100, v21, 16, 1
	v_bfe_u32 v101, v20, 16, 1
	v_bfe_u32 v102, v77, 16, 1
	v_bfe_u32 v103, v76, 16, 1
	v_add3_u32 v104, v76, v103, s33
	v_add3_u32 v105, v77, v102, s33
	v_add3_u32 v106, v20, v101, s33
	v_add3_u32 v107, v21, v100, s33
	v_bfe_u32 v20, v98, 16, 1
	v_bfe_u32 v21, v99, 16, 1
	v_bfe_u32 v76, v12, 16, 1
	v_bfe_u32 v77, v13, 16, 1
	v_add3_u32 v112, v13, v77, s33
	v_add3_u32 v12, v12, v76, s33
	v_add3_u32 v13, v99, v21, s33
	v_add3_u32 v20, v98, v20, s33
	v_lshrrev_b32_e32 v113, 16, v20
	v_lshrrev_b32_e32 v114, 16, v13
	v_lshrrev_b32_e32 v115, 16, v12
	s_waitcnt vmcnt(1)
	v_lshlrev_b32_e32 v13, 16, v17
	v_lshlrev_b32_e32 v12, 16, v16
	v_and_b32_e32 v21, 0xffff0000, v17
	v_and_b32_e32 v20, 0xffff0000, v16
	v_pk_mul_f32 v[16:17], v[12:13], v[12:13]
	v_pk_mul_f32 v[76:77], v[20:21], v[20:21]
	v_lshlrev_b32_e32 v98, 16, v18
	v_and_b32_e32 v100, 0xffff0000, v18
	v_add_f32_e32 v16, v16, v76
	v_lshlrev_b32_e32 v99, 16, v19
	v_and_b32_e32 v101, 0xffff0000, v19
	v_mov_b32_e32 v18, v100
	v_mov_b32_e32 v19, v98
	v_add_f32_e32 v16, v17, v16
	v_pk_mul_f32 v[18:19], v[18:19], v[18:19]
	v_add_f32_e32 v16, v77, v16
	v_mov_b32_e32 v102, v101
	v_mov_b32_e32 v103, v99
	v_add_f32_e32 v16, v19, v16
	v_pk_mul_f32 v[102:103], v[102:103], v[102:103]
	v_add_f32_e32 v16, v18, v16
	v_add_f32_e32 v16, v103, v16
	v_add_f32_e32 v16, v102, v16
	s_nop 1
	v_add_f32_dpp v16, v16, v16 row_ror:8 row_mask:0xf bank_mask:0xf bound_ctrl:1
	s_nop 1
	v_add_f32_dpp v16, v16, v16 row_ror:4 row_mask:0xf bank_mask:0xf bound_ctrl:1
	s_nop 1
	v_add_f32_dpp v16, v16, v16 quad_perm:[2,3,0,1] row_mask:0xf bank_mask:0xf bound_ctrl:1
	s_nop 1
	v_add_f32_dpp v16, v16, v16 quad_perm:[1,0,3,2] row_mask:0xf bank_mask:0xf bound_ctrl:1
	v_fmamk_f32 v16, v16, 0x3c000000, v205
	s_nop 1
	v_rsq_f32_e32 v76, v16
	v_lshrrev_b32_e32 v16, 16, v112
	v_and_or_b32 v17, v107, s67, v16
	v_and_or_b32 v16, v106, s67, v115
	v_and_or_b32 v19, v105, s67, v114
	v_and_or_b32 v18, v104, s67, v113
	global_store_dwordx4 v[74:75], v[16:19], off
	s_nop 1
	v_mov_b32_e32 v16, v76
	v_pk_mul_f32 v[12:13], v[16:17], v[12:13] op_sel_hi:[0,1]
	v_pk_mul_f32 v[18:19], v[16:17], v[20:21] op_sel_hi:[0,1]
	v_pk_mul_f32 v[20:21], v[16:17], v[98:99] op_sel_hi:[0,1]
	v_pk_mul_f32 v[16:17], v[16:17], v[100:101] op_sel_hi:[0,1]
	v_pk_mul_f32 v[18:19], v[22:23], v[18:19]
	v_pk_mul_f32 v[14:15], v[14:15], v[16:17]
	v_pk_mul_f32 v[20:21], v[108:109], v[20:21]
	v_mov_b32_dpp v22, v18 row_ror:8 row_mask:0xf bank_mask:0xf bound_ctrl:1
	v_mov_b32_dpp v23, v19 row_ror:8 row_mask:0xf bank_mask:0xf bound_ctrl:1
	v_pk_mul_f32 v[18:19], v[62:63], v[18:19]
	v_mov_b32_dpp v16, v14 row_ror:8 row_mask:0xf bank_mask:0xf bound_ctrl:1
	v_mov_b32_dpp v17, v15 row_ror:8 row_mask:0xf bank_mask:0xf bound_ctrl:1
; __device__ __forceinline__ unsigned pk2(float lo, float hi) { return f2bf(lo) | (f2bf(hi) << 16); }
; template <int CTRL> __device__ __forceinline__ float dpp_f(float v) { return __builtin_bit_cast(float, __builtin_amdgcn_update_dpp(0, __builtin_bit_cast(int, v), CTRL, 0xF, 0xF, true)); }
; __device__ __forceinline__ float row16_sum(float v) { v += dpp_f<0x128>(v); v += dpp_f<0x124>(v); v += dpp_f<0x4E>(v); v += dpp_f<0xB1>(v); return v; }
; template <int NIT, bool F8>
; __device__ __forceinline__ void post_segment(bf16_t* seg, const float* gain, const float (&cs)[8], const float (&sn)[8], int c, int grp, unsigned char* k8 = nullptr) {
;     const f32x4 g0 = *(const f32x4*)(gain + 8 * c), g1 = *(const f32x4*)(gain + 8 * c + 4);
;     const float g[8] = {g0[0], g0[1], g0[2], g0[3], g1[0], g1[1], g1[2], g1[3]};
;     u32x4 raw[NIT];
; #pragma unroll
;     for (int it = 0; it < NIT; ++it) raw[it] = *(const u32x4*)(seg + (it * 4 + grp) * 128 + c * 8);
; #pragma unroll
;     for (int it = 0; it < NIT; ++it) {
;         const unsigned w[4] = {raw[it].x, raw[it].y, raw[it].z, raw[it].w}; float x[8];
; #pragma unroll
;         for (int i = 0; i < 4; ++i) { x[2 * i] = bf2f(w[i] & 0xffffu); x[2 * i + 1] = __builtin_bit_cast(float, w[i] & 0xffff0000u); }
;         float ss = 0.f;
; #pragma unroll
;         for (int e = 0; e < 8; ++e) ss += x[e] * x[e];
;         ss = row16_sum(ss); const float r = 1.f / sqrtf(ss * (1.f / 128.f) + EPS);
;         float o[8];
; #pragma unroll
;         for (int e = 0; e < 8; ++e) { const float y = x[e] * r * g[e]; const float py = dpp_f<0x128>(y); o[e] = y * cs[e] + py * sn[e]; }
;         u32x4 ow; ow.x = pk2(o[0], o[1]); ow.y = pk2(o[2], o[3]); ow.z = pk2(o[4], o[5]); ow.w = pk2(o[6], o[7]);
;         if constexpr (F8) *(u32x2*)(k8 + (it * 4 + grp) * 128 + c * 8) = to_fp8x8(o);
;         else *(u32x4*)(seg + (it * 4 + grp) * 128 + c * 8) = ow;
;     }
	v_pk_mul_f32 v[12:13], v[110:111], v[12:13]
	v_pk_fma_f32 v[18:19], v[66:67], v[22:23], v[18:19]
	v_mov_b32_dpp v22, v20 row_ror:8 row_mask:0xf bank_mask:0xf bound_ctrl:1
	v_mov_b32_dpp v23, v21 row_ror:8 row_mask:0xf bank_mask:0xf bound_ctrl:1
	v_pk_mul_f32 v[16:17], v[68:69], v[16:17]
	v_mov_b32_dpp v76, v12 row_ror:8 row_mask:0xf bank_mask:0xf bound_ctrl:1
	v_mov_b32_dpp v77, v13 row_ror:8 row_mask:0xf bank_mask:0xf bound_ctrl:1
	v_pk_mul_f32 v[12:13], v[58:59], v[12:13]
	v_pk_mul_f32 v[22:23], v[72:73], v[22:23]
	v_pk_fma_f32 v[14:15], v[60:61], v[14:15], v[16:17]
	v_pk_fma_f32 v[12:13], v[70:71], v[76:77], v[12:13]
	v_pk_fma_f32 v[20:21], v[52:53], v[20:21], v[22:23]
	v_cvt_pk_bf16_f32 v12, v12, v18
	v_cvt_pk_bf16_f32 v13, v13, v19
	v_cvt_pk_bf16_f32 v15, v21, v15
	v_cvt_pk_bf16_f32 v14, v20, v14
	global_store_dwordx4 v[74:75], v[12:15], off offset:1024
	global_load_dwordx4 v[16:19], v[28:29], off
	s_nop 0
	global_load_dwordx4 v[12:15], v[28:29], off offset:16
	global_load_dwordx4 v[20:23], v[64:65], off offset:2048
	v_lshlrev_b32_e32 v75, 16, v9
	v_lshlrev_b32_e32 v74, 16, v8
	v_and_b32_e32 v9, 0xffff0000, v9
	v_and_b32_e32 v8, 0xffff0000, v8
	v_pk_mul_f32 v[76:77], v[74:75], v[74:75]
	v_pk_mul_f32 v[98:99], v[8:9], v[8:9]
	v_lshlrev_b32_e32 v100, 16, v10
	v_and_b32_e32 v10, 0xffff0000, v10
	v_add_f32_e32 v76, v76, v98
	v_mov_b32_e32 v102, v10
	v_mov_b32_e32 v103, v100
	v_add_f32_e32 v76, v77, v76
	v_lshlrev_b32_e32 v101, 16, v11
	v_and_b32_e32 v11, 0xffff0000, v11
	v_pk_mul_f32 v[102:103], v[102:103], v[102:103]
	v_add_f32_e32 v76, v99, v76
	v_mov_b32_e32 v104, v11
	v_mov_b32_e32 v105, v101
	v_add_f32_e32 v76, v103, v76
	v_pk_mul_f32 v[104:105], v[104:105], v[104:105]
	v_add_f32_e32 v76, v102, v76
	v_add_f32_e32 v76, v105, v76
	v_add_f32_e32 v76, v104, v76
	s_nop 1
	v_add_f32_dpp v76, v76, v76 row_ror:8 row_mask:0xf bank_mask:0xf bound_ctrl:1
	s_nop 1
	v_add_f32_dpp v76, v76, v76 row_ror:4 row_mask:0xf bank_mask:0xf bound_ctrl:1
	s_nop 1
	v_add_f32_dpp v76, v76, v76 quad_perm:[2,3,0,1] row_mask:0xf bank_mask:0xf bound_ctrl:1
	s_nop 1
	v_add_f32_dpp v76, v76, v76 quad_perm:[1,0,3,2] row_mask:0xf bank_mask:0xf bound_ctrl:1
	v_fmamk_f32 v76, v76, 0x3c000000, v205
	s_nop 1
	v_rsq_f32_e32 v98, v76
	s_waitcnt vmcnt(2)
	v_mov_b32_e32 v76, v16
	v_mov_b32_e32 v77, v18
	v_mov_b32_e32 v18, v17
	v_mov_b32_e32 v16, v98
	v_pk_mul_f32 v[74:75], v[16:17], v[74:75] op_sel_hi:[0,1]
	v_pk_mul_f32 v[8:9], v[16:17], v[8:9] op_sel_hi:[0,1]
	v_pk_mul_f32 v[98:99], v[16:17], v[100:101] op_sel_hi:[0,1]
	v_pk_mul_f32 v[10:11], v[16:17], v[10:11] op_sel_hi:[0,1]
	v_pk_mul_f32 v[16:17], v[76:77], v[74:75]
	v_pk_mul_f32 v[8:9], v[18:19], v[8:9]
	s_nop 0
	v_mov_b32_dpp v74, v16 row_ror:8 row_mask:0xf bank_mask:0xf bound_ctrl:1
	v_mov_b32_dpp v75, v17 row_ror:8 row_mask:0xf bank_mask:0xf bound_ctrl:1
	v_pk_mul_f32 v[16:17], v[58:59], v[16:17]
	v_mov_b32_dpp v100, v8 row_ror:8 row_mask:0xf bank_mask:0xf bound_ctrl:1
	v_pk_fma_f32 v[16:17], v[70:71], v[74:75], v[16:17]
	s_waitcnt vmcnt(1)
	v_mov_b32_e32 v75, v14
	v_mov_b32_e32 v14, v13
	v_mov_b32_dpp v101, v9 row_ror:8 row_mask:0xf bank_mask:0xf bound_ctrl:1
	v_pk_mul_f32 v[8:9], v[62:63], v[8:9]
	v_mov_b32_e32 v74, v12
	v_pk_mul_f32 v[10:11], v[14:15], v[10:11]
	v_pk_fma_f32 v[8:9], v[66:67], v[100:101], v[8:9]
	v_pk_mul_f32 v[98:99], v[74:75], v[98:99]
	v_mov_b32_dpp v100, v10 row_ror:8 row_mask:0xf bank_mask:0xf bound_ctrl:1
	v_mov_b32_dpp v101, v11 row_ror:8 row_mask:0xf bank_mask:0xf bound_ctrl:1
	v_pk_mul_f32 v[10:11], v[60:61], v[10:11]
	v_mov_b32_dpp v12, v98 row_ror:8 row_mask:0xf bank_mask:0xf bound_ctrl:1
	v_mov_b32_dpp v13, v99 row_ror:8 row_mask:0xf bank_mask:0xf bound_ctrl:1
	v_pk_mul_f32 v[98:99], v[52:53], v[98:99]
	v_pk_fma_f32 v[10:11], v[68:69], v[100:101], v[10:11]
	v_pk_fma_f32 v[12:13], v[72:73], v[12:13], v[98:99]
	v_bfe_u32 v98, v11, 16, 1
	v_bfe_u32 v99, v10, 16, 1
	v_bfe_u32 v100, v9, 16, 1
	v_bfe_u32 v101, v8, 16, 1
	v_add3_u32 v102, v8, v101, s33
	v_add3_u32 v103, v9, v100, s33
	v_add3_u32 v104, v10, v99, s33
	v_add3_u32 v105, v11, v98, s33
	v_bfe_u32 v8, v16, 16, 1
	v_bfe_u32 v9, v17, 16, 1
	v_bfe_u32 v10, v12, 16, 1
	v_bfe_u32 v11, v13, 16, 1
	v_add3_u32 v106, v13, v11, s33
	v_add3_u32 v10, v12, v10, s33
	v_add3_u32 v9, v17, v9, s33
	v_add3_u32 v8, v16, v8, s33
	s_waitcnt vmcnt(0)
; __device__ __forceinline__ unsigned pk2(float lo, float hi) { return f2bf(lo) | (f2bf(hi) << 16); }
; template <int CTRL> __device__ __forceinline__ float dpp_f(float v) { return __builtin_bit_cast(float, __builtin_amdgcn_update_dpp(0, __builtin_bit_cast(int, v), CTRL, 0xF, 0xF, true)); }
; __device__ __forceinline__ float row16_sum(float v) { v += dpp_f<0x128>(v); v += dpp_f<0x124>(v); v += dpp_f<0x4E>(v); v += dpp_f<0xB1>(v); return v; }
; template <int NIT, bool F8>
; __device__ __forceinline__ void post_segment(bf16_t* seg, const float* gain, const float (&cs)[8], const float (&sn)[8], int c, int grp, unsigned char* k8 = nullptr) {
;     const f32x4 g0 = *(const f32x4*)(gain + 8 * c), g1 = *(const f32x4*)(gain + 8 * c + 4);
;     const float g[8] = {g0[0], g0[1], g0[2], g0[3], g1[0], g1[1], g1[2], g1[3]};
;     u32x4 raw[NIT];
; #pragma unroll
;     for (int it = 0; it < NIT; ++it) raw[it] = *(const u32x4*)(seg + (it * 4 + grp) * 128 + c * 8);
; #pragma unroll
;     for (int it = 0; it < NIT; ++it) {
;         const unsigned w[4] = {raw[it].x, raw[it].y, raw[it].z, raw[it].w}; float x[8];
; #pragma unroll
;         for (int i = 0; i < 4; ++i) { x[2 * i] = bf2f(w[i] & 0xffffu); x[2 * i + 1] = __builtin_bit_cast(float, w[i] & 0xffff0000u); }
;         float ss = 0.f;
; #pragma unroll
;         for (int e = 0; e < 8; ++e) ss += x[e] * x[e];
;         ss = row16_sum(ss); const float r = 1.f / sqrtf(ss * (1.f / 128.f) + EPS);
;         float o[8];
; #pragma unroll
;         for (int e = 0; e < 8; ++e) { const float y = x[e] * r * g[e]; const float py = dpp_f<0x128>(y); o[e] = y * cs[e] + py * sn[e]; }
;         u32x4 ow; ow.x = pk2(o[0], o[1]); ow.y = pk2(o[2], o[3]); ow.z = pk2(o[4], o[5]); ow.w = pk2(o[6], o[7]);
;         if constexpr (F8) *(u32x2*)(k8 + (it * 4 + grp) * 128 + c * 8) = to_fp8x8(o);
;         else *(u32x4*)(seg + (it * 4 + grp) * 128 + c * 8) = ow;
;     }
	v_lshlrev_b32_e32 v13, 16, v21
	v_lshlrev_b32_e32 v12, 16, v20
	v_and_b32_e32 v17, 0xffff0000, v21
	v_and_b32_e32 v16, 0xffff0000, v20
	v_lshrrev_b32_e32 v107, 16, v8
	v_lshrrev_b32_e32 v108, 16, v9
	v_lshrrev_b32_e32 v109, 16, v10
	v_pk_mul_f32 v[8:9], v[12:13], v[12:13]
	v_pk_mul_f32 v[10:11], v[16:17], v[16:17]
	v_lshlrev_b32_e32 v20, 16, v22
	v_and_b32_e32 v22, 0xffff0000, v22
	v_add_f32_e32 v8, v8, v10
	v_mov_b32_e32 v98, v22
	v_mov_b32_e32 v99, v20
	v_add_f32_e32 v8, v9, v8
	v_lshlrev_b32_e32 v21, 16, v23
	v_and_b32_e32 v23, 0xffff0000, v23
	v_pk_mul_f32 v[98:99], v[98:99], v[98:99]
	v_add_f32_e32 v8, v11, v8
	v_mov_b32_e32 v100, v23
	v_mov_b32_e32 v101, v21
	v_add_f32_e32 v8, v99, v8
	v_pk_mul_f32 v[100:101], v[100:101], v[100:101]
	v_add_f32_e32 v8, v98, v8
	v_add_f32_e32 v8, v101, v8
	v_add_f32_e32 v8, v100, v8
	v_lshrrev_b32_e32 v10, 16, v106
	v_and_or_b32 v11, v105, s67, v10
	v_add_f32_dpp v8, v8, v8 row_ror:8 row_mask:0xf bank_mask:0xf bound_ctrl:1
	v_and_or_b32 v10, v104, s67, v109
	s_nop 0
	v_add_f32_dpp v8, v8, v8 row_ror:4 row_mask:0xf bank_mask:0xf bound_ctrl:1
	s_nop 1
	v_add_f32_dpp v8, v8, v8 quad_perm:[2,3,0,1] row_mask:0xf bank_mask:0xf bound_ctrl:1
	s_nop 1
	v_add_f32_dpp v8, v8, v8 quad_perm:[1,0,3,2] row_mask:0xf bank_mask:0xf bound_ctrl:1
	v_fmamk_f32 v8, v8, 0x3c000000, v205
	v_mul_f32_e32 v9, 0x4f800000, v8
	v_cmp_gt_f32_e32 vcc, s8, v8
	s_nop 1
	v_cndmask_b32_e32 v8, v8, v9, vcc
	v_sqrt_f32_e32 v9, v8
	s_nop 0
	v_add_u32_e32 v98, -1, v9
	v_fma_f32 v99, -v98, v9, v8
	v_cmp_ge_f32_e64 s[0:1], 0, v99
	v_add_u32_e32 v99, 1, v9
	s_nop 0
	v_cndmask_b32_e64 v98, v9, v98, s[0:1]
	v_fma_f32 v9, -v99, v9, v8
	v_cmp_lt_f32_e64 s[0:1], 0, v9
	s_nop 1
	v_cndmask_b32_e64 v9, v98, v99, s[0:1]
	v_mul_f32_e32 v98, 0x37800000, v9
	v_cndmask_b32_e32 v9, v9, v98, vcc
	v_cmp_class_f32_e32 vcc, v8, v206
	s_nop 1
	v_cndmask_b32_e32 v98, v9, v8, vcc
	v_div_scale_f32 v99, s[0:1], v98, v98, 1.0
	v_rcp_f32_e32 v100, v99
	v_and_or_b32 v9, v103, s67, v108
	v_and_or_b32 v8, v102, s67, v107
	global_store_dwordx4 v[64:65], v[8:11], off offset:1024
	s_mov_b32 s0, 0x3af00000
	s_nop 0
	v_fma_f32 v8, -v99, v100, 1.0
	v_fmac_f32_e32 v100, v8, v100
	v_div_scale_f32 v8, vcc, 1.0, v98, 1.0
	v_mul_f32_e32 v9, v8, v100
	v_fma_f32 v10, -v99, v9, v8
	v_fmac_f32_e32 v9, v10, v100
	v_fma_f32 v8, -v99, v9, v8
	v_div_fmas_f32 v8, v8, v100, v9
	v_div_fixup_f32 v8, v8, v98, 1.0
	v_pk_mul_f32 v[10:11], v[8:9], v[12:13] op_sel_hi:[0,1]
	v_pk_mul_f32 v[12:13], v[8:9], v[16:17] op_sel_hi:[0,1]
	v_pk_mul_f32 v[16:17], v[8:9], v[20:21] op_sel_hi:[0,1]
	v_pk_mul_f32 v[8:9], v[8:9], v[22:23] op_sel_hi:[0,1]
	v_pk_mul_f32 v[12:13], v[18:19], v[12:13]
	v_pk_mul_f32 v[8:9], v[14:15], v[8:9]
	v_pk_mul_f32 v[16:17], v[74:75], v[16:17]
	v_mov_b32_dpp v18, v12 row_ror:8 row_mask:0xf bank_mask:0xf bound_ctrl:1
	v_mov_b32_dpp v19, v13 row_ror:8 row_mask:0xf bank_mask:0xf bound_ctrl:1
	v_pk_mul_f32 v[12:13], v[62:63], v[12:13]
	v_mov_b32_dpp v14, v8 row_ror:8 row_mask:0xf bank_mask:0xf bound_ctrl:1
	v_mov_b32_dpp v15, v9 row_ror:8 row_mask:0xf bank_mask:0xf bound_ctrl:1
	v_pk_mul_f32 v[10:11], v[76:77], v[10:11]
	v_pk_fma_f32 v[12:13], v[66:67], v[18:19], v[12:13]
	v_mov_b32_dpp v18, v16 row_ror:8 row_mask:0xf bank_mask:0xf bound_ctrl:1
	v_mov_b32_dpp v19, v17 row_ror:8 row_mask:0xf bank_mask:0xf bound_ctrl:1
	v_pk_mul_f32 v[14:15], v[68:69], v[14:15]
	v_mov_b32_dpp v20, v10 row_ror:8 row_mask:0xf bank_mask:0xf bound_ctrl:1
	v_mov_b32_dpp v21, v11 row_ror:8 row_mask:0xf bank_mask:0xf bound_ctrl:1
	v_pk_mul_f32 v[10:11], v[58:59], v[10:11]
	v_pk_mul_f32 v[18:19], v[72:73], v[18:19]
	v_pk_fma_f32 v[8:9], v[60:61], v[8:9], v[14:15]
	v_pk_fma_f32 v[10:11], v[70:71], v[20:21], v[10:11]
	v_pk_fma_f32 v[16:17], v[52:53], v[16:17], v[18:19]
	v_bfe_u32 v18, v9, 16, 1
	v_bfe_u32 v19, v8, 16, 1
	v_add3_u32 v19, v8, v19, s33
	v_add3_u32 v18, v9, v18, s33
	v_cvt_pk_bf16_f32 v8, v10, v12
	v_cvt_pk_bf16_f32 v9, v11, v13
	v_bfe_u32 v12, v16, 16, 1
	v_bfe_u32 v13, v17, 16, 1
	v_add3_u32 v13, v17, v13, s33
	v_add3_u32 v12, v16, v12, s33
	v_lshrrev_b32_e32 v12, 16, v12
	v_lshrrev_b32_e32 v13, 16, v13
	v_and_or_b32 v11, v18, s67, v13
	v_and_or_b32 v10, v19, s67, v12
	global_store_dwordx4 v[64:65], v[8:11], off offset:2048
	global_load_dwordx4 v[8:11], v[30:31], off
	s_nop 0
	global_load_dwordx4 v[12:15], v[30:31], off offset:16
	v_div_fixup_f32 v16, v97, v94, 1.0
	v_mul_f32_e32 v18, v16, v78
	v_mul_f32_e32 v19, v16, v79
	v_mul_f32_e32 v20, v16, v80
	v_mul_f32_e32 v21, v16, v81
	v_mul_f32_e32 v64, v16, v82
	v_mul_f32_e32 v65, v16, v83
	v_mul_f32_e32 v70, v16, v84
	v_div_fixup_f32 v22, v96, v95, 1.0
	v_mul_f32_e32 v72, v22, v86
	v_mul_f32_e32 v73, v22, v87
	v_mul_f32_e32 v74, v22, v88
	v_mul_f32_e32 v75, v22, v89
	v_mul_f32_e32 v76, v22, v90
	v_mul_f32_e32 v77, v22, v91
	v_mul_f32_e32 v78, v22, v92
	v_mul_f32_e32 v71, v16, v85
	v_mul_f32_e32 v79, v22, v93
	v_lshl_add_u64 v[16:17], s[90:91], 0, v[44:45]
	v_lshl_add_u64 v[22:23], s[90:91], 0, v[46:47]
	s_waitcnt vmcnt(1)
	v_mul_f32_e32 v18, v8, v18
	s_nop 1
	v_mov_b32_dpp v80, v18 row_ror:8 row_mask:0xf bank_mask:0xf bound_ctrl:1
	v_mul_f32_e32 v81, v58, v18
	v_mul_f32_e32 v18, v9, v19
	v_fmac_f32_e32 v81, v54, v80
	v_mul_f32_e32 v80, v62, v18
	v_mov_b32_dpp v19, v18 row_ror:8 row_mask:0xf bank_mask:0xf bound_ctrl:1
	v_mul_f32_e32 v18, v10, v20
	v_fmac_f32_e32 v80, v66, v19
	v_mul_f32_e32 v20, v59, v18
	v_mov_b32_dpp v19, v18 row_ror:8 row_mask:0xf bank_mask:0xf bound_ctrl:1
	v_mul_f32_e32 v18, v11, v21
	v_fmac_f32_e32 v20, v56, v19
	v_mul_f32_e32 v21, v63, v18
	v_mov_b32_dpp v19, v18 row_ror:8 row_mask:0xf bank_mask:0xf bound_ctrl:1
	s_waitcnt vmcnt(0)
; __device__ __forceinline__ unsigned pk2(float lo, float hi) { return f2bf(lo) | (f2bf(hi) << 16); }
; template <int CTRL> __device__ __forceinline__ float dpp_f(float v) { return __builtin_bit_cast(float, __builtin_amdgcn_update_dpp(0, __builtin_bit_cast(int, v), CTRL, 0xF, 0xF, true)); }
; __device__ __forceinline__ u32x2 to_fp8x8(const float (&o)[8]) {
;     u32x2 w; int t0 = __builtin_amdgcn_cvt_pk_fp8_f32(o[0], o[1], 0, false); t0 = __builtin_amdgcn_cvt_pk_fp8_f32(o[2], o[3], t0, true);
;     int t1 = __builtin_amdgcn_cvt_pk_fp8_f32(o[4], o[5], 0, false); t1 = __builtin_amdgcn_cvt_pk_fp8_f32(o[6], o[7], t1, true); w.x = (unsigned)t0; w.y = (unsigned)t1; return w;
; }
; template <int NIT, bool F8>
; __device__ __forceinline__ void post_segment(bf16_t* seg, const float* gain, const float (&cs)[8], const float (&sn)[8], int c, int grp, unsigned char* k8 = nullptr) {
;     ...
;         for (int e = 0; e < 8; ++e) { const float y = x[e] * r * g[e]; const float py = dpp_f<0x128>(y); o[e] = y * cs[e] + py * sn[e]; }
;         u32x4 ow; ow.x = pk2(o[0], o[1]); ow.y = pk2(o[2], o[3]); ow.z = pk2(o[4], o[5]); ow.w = pk2(o[6], o[7]);
;         if constexpr (F8) *(u32x2*)(k8 + (it * 4 + grp) * 128 + c * 8) = to_fp8x8(o);
;         else *(u32x4*)(seg + (it * 4 + grp) * 128 + c * 8) = ow;
;     }
; __device__ __forceinline__ void post_token(int pos, const float* gaq, const float* gak, const float* gbq, const float* gbk, const float* gik, ...
;     ...
;     float ci[4], si[4];
; #pragma unroll
;     for (int e = 0; e < 4; ++e) { float s_; rope_cs(pf * INVF[2 * ((4 * c + e) & 31)], ci[e], s_); si[e] = s_ * sgn; }
;     f32x4 xi[4];
; #pragma unroll
;     for (int it = 0; it < 4; ++it) xi[it] = *(const f32x4*)(irow + (it * 4 + grp) * 64 + 4 * c);
;     const f32x4 xk = *(const f32x4*)(irow + 1024 + 4 * c);
; #pragma unroll
;     for (int it = 0; it < 4; ++it) { float o[4];
; #pragma unroll
;         for (int e = 0; e < 4; ++e) { const float x = xi[it][e]; const float px = dpp_f<0x128>(x); o[e] = x * ci[e] + px * si[e]; }
;         u32x2 ow; ow.x = pk2(o[0], o[1]); ow.y = pk2(o[2], o[3]); *(u32x2*)(iq + (it * 4 + grp) * 64 + 4 * c) = ow; }
	v_mul_f32_e32 v18, v12, v64
	v_fmac_f32_e32 v21, v67, v19
	v_mul_f32_e32 v64, v52, v18
	v_mov_b32_dpp v19, v18 row_ror:8 row_mask:0xf bank_mask:0xf bound_ctrl:1
	v_mul_f32_e32 v18, v13, v65
	v_fmac_f32_e32 v64, v55, v19
	v_mul_f32_e32 v65, v60, v18
	v_mov_b32_dpp v19, v18 row_ror:8 row_mask:0xf bank_mask:0xf bound_ctrl:1
	v_mul_f32_e32 v18, v14, v70
	v_fmac_f32_e32 v65, v68, v19
	v_mul_f32_e32 v70, v53, v18
	v_mov_b32_dpp v19, v18 row_ror:8 row_mask:0xf bank_mask:0xf bound_ctrl:1
	v_mov_b32_e32 v18, 0
	v_cvt_pk_fp8_f32 v18, v81, v80
	v_mul_f32_e32 v8, v8, v72
	v_fmac_f32_e32 v70, v57, v19
	v_mov_b32_e32 v19, 0
	v_cvt_pk_fp8_f32 v18, v20, v21 op_sel:[0,0,1]
	v_mov_b32_dpp v20, v8 row_ror:8 row_mask:0xf bank_mask:0xf bound_ctrl:1
	v_mul_f32_e32 v21, v58, v8
	v_mul_f32_e32 v8, v9, v73
	v_fmac_f32_e32 v21, v54, v20
	v_mul_f32_e32 v20, v62, v8
	v_mov_b32_dpp v9, v8 row_ror:8 row_mask:0xf bank_mask:0xf bound_ctrl:1
	v_mul_f32_e32 v8, v10, v74
	v_fmac_f32_e32 v20, v66, v9
	v_mul_f32_e32 v10, v59, v8
	v_mov_b32_dpp v9, v8 row_ror:8 row_mask:0xf bank_mask:0xf bound_ctrl:1
	v_mul_f32_e32 v8, v11, v75
	v_fmac_f32_e32 v10, v56, v9
	v_mul_f32_e32 v11, v63, v8
	v_mov_b32_dpp v9, v8 row_ror:8 row_mask:0xf bank_mask:0xf bound_ctrl:1
	v_mul_f32_e32 v8, v12, v76
	v_fmac_f32_e32 v11, v67, v9
	v_mul_f32_e32 v12, v52, v8
	v_mov_b32_dpp v9, v8 row_ror:8 row_mask:0xf bank_mask:0xf bound_ctrl:1
	v_mul_f32_e32 v8, v13, v77
	v_fmac_f32_e32 v12, v55, v9
	v_mul_f32_e32 v13, v60, v8
	v_mov_b32_dpp v9, v8 row_ror:8 row_mask:0xf bank_mask:0xf bound_ctrl:1
	v_mul_f32_e32 v8, v14, v78
	v_cvt_pk_fp8_f32 v19, v64, v65
	v_fmac_f32_e32 v13, v68, v9
	v_mul_f32_dpp v14, v8, v57 row_ror:8 row_mask:0xf bank_mask:0xf bound_ctrl:1
	v_fmac_f32_e32 v14, v53, v8
	v_mov_b32_e32 v8, 0
	v_mov_b32_e32 v9, 0
	v_mul_f32_e32 v71, v15, v71
	v_cvt_pk_fp8_f32 v8, v21, v20
	v_cvt_pk_fp8_f32 v9, v12, v13
	v_mov_b32_dpp v82, v71 row_ror:8 row_mask:0xf bank_mask:0xf bound_ctrl:1
	v_mul_f32_e32 v64, v61, v71
	v_mul_f32_e32 v15, v15, v79
	v_fmac_f32_e32 v64, v69, v82
	v_cvt_pk_fp8_f32 v19, v70, v64 op_sel:[0,0,1]
	v_mul_f32_dpp v12, v15, v69 row_ror:8 row_mask:0xf bank_mask:0xf bound_ctrl:1
	v_fmac_f32_e32 v12, v61, v15
	v_cvt_pk_fp8_f32 v8, v10, v11 op_sel:[0,0,1]
	v_cvt_pk_fp8_f32 v9, v14, v12 op_sel:[0,0,1]
	v_add_co_u32_e32 v10, vcc, s0, v16
	s_nop 1
	v_addc_co_u32_e32 v11, vcc, 0, v17, vcc
	s_lshl_b32 s98, s10, 7
	s_add_u32 s98, s98, 0x3cf00000
	s_add_u32 s98, s90, s98
	s_addc_u32 s99, s91, 0
	s_add_u32 s100, s98, 0x800000
	s_addc_u32 s101, s99, 0
	v_lshrrev_b32_e32 v122, 4, v182
	v_and_b32_e32 v123, 15, v182
	v_lshlrev_b32_e32 v122, 21, v122
	v_lshl_or_b32 v122, v123, 3, v122
	global_store_dwordx2 v122, v[18:19], s[98:99]
	global_store_dwordx2 v122, v[8:9], s[100:101]
	global_load_dwordx4 v[10:13], v[22:23], off offset:-2048
	s_nop 0
	global_load_dwordx4 v[14:17], v[22:23], off offset:-1024
	global_load_dwordx4 v[18:21], v[22:23], off
	global_load_dwordx4 v[60:63], v[22:23], off offset:1024
	v_lshl_add_u64 v[8:9], s[90:91], 0, v[48:49]
	global_load_dwordx4 v[64:67], v[8:9], off
	v_mov_b32_e32 v9, v52
	v_mov_b32_e32 v52, v59
	v_mov_b32_e32 v8, v58
	v_lshl_add_u64 v[22:23], s[90:91], 0, v[42:43]
	s_waitcnt vmcnt(4)
	v_mov_b32_dpp v70, v11 row_ror:8 row_mask:0xf bank_mask:0xf bound_ctrl:1
	v_mov_b32_dpp v71, v13 row_ror:8 row_mask:0xf bank_mask:0xf bound_ctrl:1
	v_mov_b32_dpp v68, v10 row_ror:8 row_mask:0xf bank_mask:0xf bound_ctrl:1
	v_mov_b32_dpp v69, v12 row_ror:8 row_mask:0xf bank_mask:0xf bound_ctrl:1
	v_mov_b32_e32 v72, v10
	v_mov_b32_e32 v73, v12
	v_mov_b32_e32 v12, v11
	v_pk_mul_f32 v[10:11], v[56:57], v[70:71]
	v_pk_mul_f32 v[68:69], v[54:55], v[68:69]
	v_pk_fma_f32 v[10:11], v[12:13], v[52:53], v[10:11]
	v_pk_fma_f32 v[68:69], v[72:73], v[8:9], v[68:69]
	v_cvt_pk_bf16_f32 v11, v69, v11
	v_cvt_pk_bf16_f32 v10, v68, v10
	global_store_dwordx2 v[22:23], v[10:11], off offset:-1024
	s_waitcnt vmcnt(4)
	v_mov_b32_dpp v11, v16 row_ror:8 row_mask:0xf bank_mask:0xf bound_ctrl:1
	v_mov_b32_dpp v10, v14 row_ror:8 row_mask:0xf bank_mask:0xf bound_ctrl:1
	v_mov_b32_dpp v12, v15 row_ror:8 row_mask:0xf bank_mask:0xf bound_ctrl:1
	v_mov_b32_dpp v13, v17 row_ror:8 row_mask:0xf bank_mask:0xf bound_ctrl:1
	v_mov_b32_e32 v58, v14
	v_mov_b32_e32 v59, v16
	v_pk_mul_f32 v[10:11], v[54:55], v[10:11]
	v_mov_b32_e32 v16, v15
	v_pk_fma_f32 v[10:11], v[58:59], v[8:9], v[10:11]
	v_pk_mul_f32 v[12:13], v[56:57], v[12:13]
	v_pk_fma_f32 v[12:13], v[16:17], v[52:53], v[12:13]
	v_cvt_pk_bf16_f32 v11, v11, v13
	v_cvt_pk_bf16_f32 v10, v10, v12
	global_store_dwordx2 v[22:23], v[10:11], off offset:-512
	s_waitcnt vmcnt(4)
; __device__ __forceinline__ unsigned pk2(float lo, float hi) { return f2bf(lo) | (f2bf(hi) << 16); }
; template <int CTRL> __device__ __forceinline__ float dpp_f(float v) { return __builtin_bit_cast(float, __builtin_amdgcn_update_dpp(0, __builtin_bit_cast(int, v), CTRL, 0xF, 0xF, true)); }
; __device__ __forceinline__ float row16_sum(float v) { v += dpp_f<0x128>(v); v += dpp_f<0x124>(v); v += dpp_f<0x4E>(v); v += dpp_f<0xB1>(v); return v; }
; __device__ __forceinline__ void post_token(int pos, const float* gaq, const float* gak, const float* gbq, const float* gbk, const float* gik, ...
;     ...
;     for (int it = 0; it < 4; ++it) { float o[4];
; #pragma unroll
;         for (int e = 0; e < 4; ++e) { const float x = xi[it][e]; const float px = dpp_f<0x128>(x); o[e] = x * ci[e] + px * si[e]; }
;         u32x2 ow; ow.x = pk2(o[0], o[1]); ow.y = pk2(o[2], o[3]); *(u32x2*)(iq + (it * 4 + grp) * 64 + 4 * c) = ow; }
;     { const f32x4 gk = *(const f32x4*)(gik + 4 * c);
;       float ss = (xk[0] * xk[0] + xk[1] * xk[1]) + (xk[2] * xk[2] + xk[3] * xk[3]); ss = row16_sum(ss); const float r = 1.f / sqrtf(ss * (1.f / 64.f) + EPS);
;       float o[4];
; #pragma unroll
;       for (int e = 0; e < 4; ++e) { const float y = xk[e] * r * gk[e]; const float py = dpp_f<0x128>(y); o[e] = y * ci[e] + py * si[e]; }
;       if (grp == 0) { u32x2 ow; ow.x = pk2(o[0], o[1]); ow.y = pk2(o[2], o[3]); *(u32x2*)(ik + 4 * c) = ow; } }
;     if (lane < 16) iw[lane] = irow[1088 + lane] * 0.25f;
	v_mov_b32_dpp v11, v20 row_ror:8 row_mask:0xf bank_mask:0xf bound_ctrl:1
	v_mov_b32_dpp v10, v18 row_ror:8 row_mask:0xf bank_mask:0xf bound_ctrl:1
	v_mov_b32_dpp v12, v19 row_ror:8 row_mask:0xf bank_mask:0xf bound_ctrl:1
	v_mov_b32_dpp v13, v21 row_ror:8 row_mask:0xf bank_mask:0xf bound_ctrl:1
	v_mov_b32_e32 v14, v18
	v_mov_b32_e32 v15, v20
	v_pk_mul_f32 v[10:11], v[54:55], v[10:11]
	v_mov_b32_e32 v20, v19
	v_pk_fma_f32 v[10:11], v[8:9], v[14:15], v[10:11]
	v_pk_mul_f32 v[12:13], v[56:57], v[12:13]
	v_pk_fma_f32 v[12:13], v[20:21], v[52:53], v[12:13]
	v_cvt_pk_bf16_f32 v11, v11, v13
	v_cvt_pk_bf16_f32 v10, v10, v12
	global_store_dwordx2 v[22:23], v[10:11], off
	s_waitcnt vmcnt(4)
	v_mov_b32_dpp v11, v62 row_ror:8 row_mask:0xf bank_mask:0xf bound_ctrl:1
	v_mov_b32_dpp v10, v60 row_ror:8 row_mask:0xf bank_mask:0xf bound_ctrl:1
	v_mov_b32_dpp v12, v61 row_ror:8 row_mask:0xf bank_mask:0xf bound_ctrl:1
	v_mov_b32_dpp v13, v63 row_ror:8 row_mask:0xf bank_mask:0xf bound_ctrl:1
	v_mov_b32_e32 v14, v60
	v_mov_b32_e32 v15, v62
	v_pk_mul_f32 v[10:11], v[54:55], v[10:11]
	v_mov_b32_e32 v62, v61
	v_pk_fma_f32 v[10:11], v[8:9], v[14:15], v[10:11]
	v_pk_mul_f32 v[12:13], v[56:57], v[12:13]
	v_pk_fma_f32 v[12:13], v[52:53], v[62:63], v[12:13]
	v_cvt_pk_bf16_f32 v11, v11, v13
	v_cvt_pk_bf16_f32 v10, v10, v12
	global_store_dwordx2 v[22:23], v[10:11], off offset:512
	global_load_dwordx4 v[14:17], v[32:33], off
	s_waitcnt vmcnt(5)
	v_pk_mul_f32 v[10:11], v[66:67], v[66:67]
	v_pk_mul_f32 v[12:13], v[64:65], v[64:65]
	s_nop 0
	v_pk_mov_b32 v[18:19], v[12:13], v[10:11] op_sel:[1,0]
	v_mov_b32_e32 v13, v11
	v_pk_add_f32 v[10:11], v[18:19], v[12:13]
	s_nop 0
	v_add_f32_e32 v10, v10, v11
	s_nop 1
	v_add_f32_dpp v10, v10, v10 row_ror:8 row_mask:0xf bank_mask:0xf bound_ctrl:1
	s_nop 1
	v_add_f32_dpp v10, v10, v10 row_ror:4 row_mask:0xf bank_mask:0xf bound_ctrl:1
	s_nop 1
	v_add_f32_dpp v10, v10, v10 quad_perm:[2,3,0,1] row_mask:0xf bank_mask:0xf bound_ctrl:1
	s_nop 1
	v_add_f32_dpp v10, v10, v10 quad_perm:[1,0,3,2] row_mask:0xf bank_mask:0xf bound_ctrl:1
	v_fmamk_f32 v10, v10, 0x3c800000, v205
	v_mul_f32_e32 v11, 0x4f800000, v10
	v_cmp_gt_f32_e32 vcc, s8, v10
	s_nop 1
	v_cndmask_b32_e32 v10, v10, v11, vcc
	v_sqrt_f32_e32 v11, v10
	s_nop 0
	v_add_u32_e32 v12, -1, v11
	v_fma_f32 v13, -v12, v11, v10
	v_cmp_ge_f32_e64 s[0:1], 0, v13
	v_add_u32_e32 v13, 1, v11
	s_nop 0
	v_cndmask_b32_e64 v12, v11, v12, s[0:1]
	v_fma_f32 v11, -v13, v11, v10
	v_cmp_lt_f32_e64 s[0:1], 0, v11
	s_nop 1
	v_cndmask_b32_e64 v11, v12, v13, s[0:1]
	v_mul_f32_e32 v12, 0x37800000, v11
	v_cndmask_b32_e32 v11, v11, v12, vcc
	v_cmp_class_f32_e32 vcc, v10, v206
	s_nop 1
	v_cndmask_b32_e32 v10, v11, v10, vcc
	v_div_scale_f32 v11, s[0:1], v10, v10, 1.0
	v_rcp_f32_e32 v12, v11
	s_nop 0
	v_fma_f32 v13, -v11, v12, 1.0
	v_fmac_f32_e32 v12, v13, v12
	v_div_scale_f32 v13, vcc, 1.0, v10, 1.0
	v_mul_f32_e32 v18, v13, v12
	v_fma_f32 v19, -v11, v18, v13
	v_fmac_f32_e32 v18, v19, v12
	v_fma_f32 v11, -v11, v18, v13
	v_div_fmas_f32 v11, v11, v12, v18
	v_div_fixup_f32 v18, v11, v10, 1.0
	v_mov_b32_e32 v10, v64
	v_mov_b32_e32 v11, v66
	v_mov_b32_e32 v66, v65
	v_pk_mul_f32 v[10:11], v[10:11], v[18:19] op_sel_hi:[1,0]
	v_pk_mul_f32 v[18:19], v[66:67], v[18:19] op_sel_hi:[1,0]
	s_waitcnt vmcnt(0)
	v_mov_b32_e32 v12, v14
	v_mov_b32_e32 v13, v16
	v_mov_b32_e32 v16, v15
	v_pk_mul_f32 v[12:13], v[12:13], v[10:11]
	v_pk_mul_f32 v[16:17], v[16:17], v[18:19]
	s_nop 0
	v_mov_b32_dpp v10, v12 row_ror:8 row_mask:0xf bank_mask:0xf bound_ctrl:1
	v_mov_b32_dpp v14, v16 row_ror:8 row_mask:0xf bank_mask:0xf bound_ctrl:1
	v_mov_b32_dpp v11, v13 row_ror:8 row_mask:0xf bank_mask:0xf bound_ctrl:1
	v_mov_b32_dpp v15, v17 row_ror:8 row_mask:0xf bank_mask:0xf bound_ctrl:1
	s_and_saveexec_b64 s[0:1], s[38:39]
	s_cbranch_execz .LBB0_1007
	v_pk_mul_f32 v[8:9], v[8:9], v[12:13]
	v_pk_mul_f32 v[16:17], v[52:53], v[16:17]
	v_pk_fma_f32 v[8:9], v[54:55], v[10:11], v[8:9]
	v_pk_fma_f32 v[12:13], v[56:57], v[14:15], v[16:17]
	v_cvt_pk_bf16_f32 v9, v9, v13
	v_cvt_pk_bf16_f32 v8, v8, v12
	v_lshl_add_u64 v[10:11], s[90:91], 0, v[38:39]
	global_store_dwordx2 v[10:11], v[8:9], off
	v_lshl_add_u64 v[8:9], s[90:91], 0, v[50:51]
	global_load_dword v10, v[8:9], off
	v_lshl_add_u64 v[8:9], s[90:91], 0, v[36:37]
	s_waitcnt vmcnt(0)
	v_mul_f32_e32 v10, 0x3e800000, v10
	global_store_dword v[8:9], v10, off
	s_branch .LBB0_1007
